# wi 11/21 + all GEMM K-loops: MFMA order changed so the two accumulations of each accumulator are adjacent
# speedup vs baseline: 1.0075x; 1.0072x over previous
.LBB0_256:
	v_add_u32_e32 v172, s70, v160
	v_add_u32_e32 v188, s71, v160
	ds_read_b128 v[154:157], v172
	ds_read_b128 v[164:167], v172 offset:1024
	ds_read_b128 v[168:171], v172 offset:2048
	ds_read_b128 v[172:175], v172 offset:3072
	ds_read_b128 v[176:179], v188
	ds_read_b128 v[180:183], v188 offset:1024
	ds_read_b128 v[184:187], v188 offset:2048
	ds_read_b128 v[188:191], v188 offset:3072
	s_add_i32 s75, s30, 2
	s_add_u32 s31, s28, 0xfffc0080
	s_addc_u32 s34, s29, -1
	s_cmp_eq_u32 s67, s30
	s_cselect_b32 s30, s26, s17
	s_cselect_b32 s35, s25, s34
	s_cselect_b32 s34, s24, s31
	s_cselect_b32 s31, s27, s19
	v_lshl_add_u64 v[224:225], s[28:29], 0, v[146:147]
	s_add_i32 m0, s58, 0xc000
	ds_read_b128 v[192:195], v163
	ds_read_b128 v[196:199], v163 offset:1024
	ds_read_b128 v[200:203], v163 offset:2048
	ds_read_b128 v[204:207], v163 offset:3072
	ds_read_b128 v[208:211], v163 offset:4096
	ds_read_b128 v[212:215], v163 offset:5120
	ds_read_b128 v[216:219], v163 offset:6144
	ds_read_b128 v[220:223], v163 offset:7168
	global_load_lds_dwordx4 v[224:225], off
	v_lshl_add_u64 v[224:225], s[28:29], 0, v[148:149]
	s_add_i32 m0, s58, 0xe000
	s_nop 0
	global_load_lds_dwordx4 v[224:225], off
	s_waitcnt vmcnt(8)
	s_waitcnt lgkmcnt(0)
	s_barrier
	v_mfma_f32_16x16x32_bf16 v[42:45], v[154:157], v[192:195], v[42:45]
	v_mfma_f32_16x16x32_bf16 v[42:45], v[164:167], v[196:199], v[42:45]
	v_mfma_f32_16x16x32_bf16 v[26:29], v[168:171], v[192:195], v[26:29]
	v_mfma_f32_16x16x32_bf16 v[26:29], v[172:175], v[196:199], v[26:29]
	v_mfma_f32_16x16x32_bf16 v[54:57], v[154:157], v[200:203], v[54:57]
	v_mfma_f32_16x16x32_bf16 v[54:57], v[164:167], v[204:207], v[54:57]
	v_mfma_f32_16x16x32_bf16 v[38:41], v[168:171], v[200:203], v[38:41]
	v_mfma_f32_16x16x32_bf16 v[38:41], v[172:175], v[204:207], v[38:41]
	v_mfma_f32_16x16x32_bf16 v[66:69], v[154:157], v[208:211], v[66:69]
	v_mfma_f32_16x16x32_bf16 v[66:69], v[164:167], v[212:215], v[66:69]
	v_mfma_f32_16x16x32_bf16 v[50:53], v[168:171], v[208:211], v[50:53]
	v_mfma_f32_16x16x32_bf16 v[50:53], v[172:175], v[212:215], v[50:53]
	v_mfma_f32_16x16x32_bf16 v[62:65], v[154:157], v[216:219], v[62:65]
	v_mfma_f32_16x16x32_bf16 v[62:65], v[164:167], v[220:223], v[62:65]
	v_mfma_f32_16x16x32_bf16 v[46:49], v[168:171], v[216:219], v[46:49]
	v_mfma_f32_16x16x32_bf16 v[46:49], v[172:175], v[220:223], v[46:49]
	v_mfma_f32_16x16x32_bf16 v[14:17], v[176:179], v[192:195], v[14:17]
	v_mfma_f32_16x16x32_bf16 v[14:17], v[180:183], v[196:199], v[14:17]
	v_mfma_f32_16x16x32_bf16 v[2:5], v[184:187], v[192:195], v[2:5]
	v_mfma_f32_16x16x32_bf16 v[2:5], v[188:191], v[196:199], v[2:5]
	v_mfma_f32_16x16x32_bf16 v[22:25], v[176:179], v[200:203], v[22:25]
	v_mfma_f32_16x16x32_bf16 v[22:25], v[180:183], v[204:207], v[22:25]
	v_mfma_f32_16x16x32_bf16 v[6:9], v[184:187], v[200:203], v[6:9]
	v_mfma_f32_16x16x32_bf16 v[6:9], v[188:191], v[204:207], v[6:9]
	v_mfma_f32_16x16x32_bf16 v[30:33], v[176:179], v[208:211], v[30:33]
	v_mfma_f32_16x16x32_bf16 v[30:33], v[180:183], v[212:215], v[30:33]
	v_mfma_f32_16x16x32_bf16 v[10:13], v[184:187], v[208:211], v[10:13]
	v_mfma_f32_16x16x32_bf16 v[10:13], v[188:191], v[212:215], v[10:13]
	v_mfma_f32_16x16x32_bf16 v[34:37], v[176:179], v[216:219], v[34:37]
	v_mfma_f32_16x16x32_bf16 v[34:37], v[180:183], v[220:223], v[34:37]
	v_mfma_f32_16x16x32_bf16 v[18:21], v[184:187], v[216:219], v[18:21]
	v_mfma_f32_16x16x32_bf16 v[18:21], v[188:191], v[220:223], v[18:21]
	s_barrier
	s_add_i32 s50, s70, s54
	v_lshl_add_u64 v[224:225], s[30:31], 0, v[134:135]
	s_mov_b32 m0, s50
	ds_read_b128 v[192:195], v163 offset:16384
	ds_read_b128 v[196:199], v163 offset:17408
	ds_read_b128 v[200:203], v163 offset:18432
	ds_read_b128 v[204:207], v163 offset:19456
	ds_read_b128 v[208:211], v163 offset:20480
	ds_read_b128 v[212:215], v163 offset:21504
	ds_read_b128 v[216:219], v163 offset:22528
	ds_read_b128 v[220:223], v163 offset:23552
	global_load_lds_dwordx4 v[224:225], off
	s_add_i32 m0, s50, 0x2000
	s_add_u32 s76, s30, 0x40000
	v_lshl_add_u64 v[226:227], s[30:31], 0, v[130:131]
	s_addc_u32 s77, s31, 0
	s_add_i32 s50, s71, s54
	global_load_lds_dwordx4 v[226:227], off
	v_lshl_add_u64 v[228:229], s[76:77], 0, v[134:135]
	s_mov_b32 m0, s50
	v_lshl_add_u64 v[230:231], s[34:35], 0, v[132:133]
	global_load_lds_dwordx4 v[228:229], off
	v_lshl_add_u64 v[228:229], s[76:77], 0, v[130:131]
	s_add_i32 m0, s50, 0x2000
	s_nop 0
	global_load_lds_dwordx4 v[228:229], off
	v_lshl_add_u64 v[228:229], s[34:35], 0, v[136:137]
	s_mov_b32 m0, s58
	s_nop 0
	global_load_lds_dwordx4 v[228:229], off
	s_mov_b32 m0, s59
	s_nop 0
	global_load_lds_dwordx4 v[230:231], off
	s_waitcnt vmcnt(8)
	s_waitcnt lgkmcnt(0)
	s_barrier
	v_mfma_f32_16x16x32_bf16 v[110:113], v[154:157], v[192:195], v[110:113]
	v_mfma_f32_16x16x32_bf16 v[110:113], v[164:167], v[196:199], v[110:113]
	v_mfma_f32_16x16x32_bf16 v[86:89], v[168:171], v[192:195], v[86:89]
	v_mfma_f32_16x16x32_bf16 v[86:89], v[172:175], v[196:199], v[86:89]
	v_mfma_f32_16x16x32_bf16 v[106:109], v[154:157], v[200:203], v[106:109]
	v_mfma_f32_16x16x32_bf16 v[106:109], v[164:167], v[204:207], v[106:109]
	v_mfma_f32_16x16x32_bf16 v[82:85], v[168:171], v[200:203], v[82:85]
	v_mfma_f32_16x16x32_bf16 v[82:85], v[172:175], v[204:207], v[82:85]
	v_mfma_f32_16x16x32_bf16 v[118:121], v[154:157], v[208:211], v[118:121]
	v_mfma_f32_16x16x32_bf16 v[118:121], v[164:167], v[212:215], v[118:121]
	v_mfma_f32_16x16x32_bf16 v[94:97], v[168:171], v[208:211], v[94:97]
	v_mfma_f32_16x16x32_bf16 v[94:97], v[172:175], v[212:215], v[94:97]
	v_mfma_f32_16x16x32_bf16 v[126:129], v[154:157], v[216:219], v[126:129]
	v_mfma_f32_16x16x32_bf16 v[126:129], v[164:167], v[220:223], v[126:129]
	v_mfma_f32_16x16x32_bf16 v[102:105], v[168:171], v[216:219], v[102:105]
	v_mfma_f32_16x16x32_bf16 v[102:105], v[172:175], v[220:223], v[102:105]
	v_mfma_f32_16x16x32_bf16 v[70:73], v[176:179], v[192:195], v[70:73]
	v_mfma_f32_16x16x32_bf16 v[70:73], v[180:183], v[196:199], v[70:73]
	v_mfma_f32_16x16x32_bf16 v[58:61], v[184:187], v[192:195], v[58:61]
	v_mfma_f32_16x16x32_bf16 v[58:61], v[188:191], v[196:199], v[58:61]
	v_mfma_f32_16x16x32_bf16 v[74:77], v[176:179], v[200:203], v[74:77]
	v_mfma_f32_16x16x32_bf16 v[74:77], v[180:183], v[204:207], v[74:77]
	v_mfma_f32_16x16x32_bf16 v[78:81], v[184:187], v[200:203], v[78:81]
	v_mfma_f32_16x16x32_bf16 v[78:81], v[188:191], v[204:207], v[78:81]
	v_mfma_f32_16x16x32_bf16 v[114:117], v[176:179], v[208:211], v[114:117]
	v_mfma_f32_16x16x32_bf16 v[114:117], v[180:183], v[212:215], v[114:117]
	v_mfma_f32_16x16x32_bf16 v[90:93], v[184:187], v[208:211], v[90:93]
	v_mfma_f32_16x16x32_bf16 v[90:93], v[188:191], v[212:215], v[90:93]
	v_mfma_f32_16x16x32_bf16 v[122:125], v[176:179], v[216:219], v[122:125]
	v_mfma_f32_16x16x32_bf16 v[122:125], v[180:183], v[220:223], v[122:125]
	v_mfma_f32_16x16x32_bf16 v[98:101], v[184:187], v[216:219], v[98:101]
	v_mfma_f32_16x16x32_bf16 v[98:101], v[188:191], v[220:223], v[98:101]
	s_barrier
	s_add_i32 s50, 0, 0x18000
	s_add_i32 s51, 0, 0x1c000
	v_add_u32_e32 v172, s50, v160
	v_add_u32_e32 v188, s51, v160
	ds_read_b128 v[154:157], v172
	ds_read_b128 v[164:167], v172 offset:1024
	ds_read_b128 v[168:171], v172 offset:2048
	ds_read_b128 v[172:175], v172 offset:3072
	ds_read_b128 v[176:179], v188
	ds_read_b128 v[180:183], v188 offset:1024
	ds_read_b128 v[184:187], v188 offset:2048
	ds_read_b128 v[188:191], v188 offset:3072
	s_add_u32 s34, s34, 0x40000
	s_addc_u32 s35, s35, 0
	s_mov_b32 m0, s60
	v_lshl_add_u64 v[232:233], s[34:35], 0, v[136:137]
	ds_read_b128 v[192:195], v163 offset:32768
	ds_read_b128 v[196:199], v163 offset:33792
	ds_read_b128 v[200:203], v163 offset:34816
	ds_read_b128 v[204:207], v163 offset:35840
	ds_read_b128 v[208:211], v163 offset:36864
	ds_read_b128 v[212:215], v163 offset:37888
	ds_read_b128 v[216:219], v163 offset:38912
	ds_read_b128 v[220:223], v163 offset:39936
	global_load_lds_dwordx4 v[232:233], off
	v_lshl_add_u64 v[232:233], s[34:35], 0, v[132:133]
	s_mov_b32 m0, s61
	s_nop 0
	global_load_lds_dwordx4 v[232:233], off
	s_waitcnt vmcnt(8)
	s_waitcnt lgkmcnt(0)
	s_barrier
	v_mfma_f32_16x16x32_bf16 v[42:45], v[154:157], v[192:195], v[42:45]
	v_mfma_f32_16x16x32_bf16 v[42:45], v[164:167], v[196:199], v[42:45]
	v_mfma_f32_16x16x32_bf16 v[26:29], v[168:171], v[192:195], v[26:29]
	v_mfma_f32_16x16x32_bf16 v[26:29], v[172:175], v[196:199], v[26:29]
	v_mfma_f32_16x16x32_bf16 v[54:57], v[154:157], v[200:203], v[54:57]
	v_mfma_f32_16x16x32_bf16 v[54:57], v[164:167], v[204:207], v[54:57]
	v_mfma_f32_16x16x32_bf16 v[38:41], v[168:171], v[200:203], v[38:41]
	v_mfma_f32_16x16x32_bf16 v[38:41], v[172:175], v[204:207], v[38:41]
	v_mfma_f32_16x16x32_bf16 v[66:69], v[154:157], v[208:211], v[66:69]
	v_mfma_f32_16x16x32_bf16 v[66:69], v[164:167], v[212:215], v[66:69]
	v_mfma_f32_16x16x32_bf16 v[50:53], v[168:171], v[208:211], v[50:53]
	v_mfma_f32_16x16x32_bf16 v[50:53], v[172:175], v[212:215], v[50:53]
	v_mfma_f32_16x16x32_bf16 v[62:65], v[154:157], v[216:219], v[62:65]
	v_mfma_f32_16x16x32_bf16 v[62:65], v[164:167], v[220:223], v[62:65]
	v_mfma_f32_16x16x32_bf16 v[46:49], v[168:171], v[216:219], v[46:49]
	v_mfma_f32_16x16x32_bf16 v[46:49], v[172:175], v[220:223], v[46:49]
	v_mfma_f32_16x16x32_bf16 v[14:17], v[176:179], v[192:195], v[14:17]
	v_mfma_f32_16x16x32_bf16 v[14:17], v[180:183], v[196:199], v[14:17]
	v_mfma_f32_16x16x32_bf16 v[2:5], v[184:187], v[192:195], v[2:5]
	v_mfma_f32_16x16x32_bf16 v[2:5], v[188:191], v[196:199], v[2:5]
	v_mfma_f32_16x16x32_bf16 v[22:25], v[176:179], v[200:203], v[22:25]
	v_mfma_f32_16x16x32_bf16 v[22:25], v[180:183], v[204:207], v[22:25]
	v_mfma_f32_16x16x32_bf16 v[6:9], v[184:187], v[200:203], v[6:9]
	v_mfma_f32_16x16x32_bf16 v[6:9], v[188:191], v[204:207], v[6:9]
	v_mfma_f32_16x16x32_bf16 v[30:33], v[176:179], v[208:211], v[30:33]
	v_mfma_f32_16x16x32_bf16 v[30:33], v[180:183], v[212:215], v[30:33]
	v_mfma_f32_16x16x32_bf16 v[10:13], v[184:187], v[208:211], v[10:13]
	v_mfma_f32_16x16x32_bf16 v[10:13], v[188:191], v[212:215], v[10:13]
	v_mfma_f32_16x16x32_bf16 v[34:37], v[176:179], v[216:219], v[34:37]
	v_mfma_f32_16x16x32_bf16 v[34:37], v[180:183], v[220:223], v[34:37]
	v_mfma_f32_16x16x32_bf16 v[18:21], v[184:187], v[216:219], v[18:21]
	v_mfma_f32_16x16x32_bf16 v[18:21], v[188:191], v[220:223], v[18:21]
	s_barrier
	s_add_i32 s34, s50, s54
	v_lshl_add_u64 v[224:225], v[224:225], 0, s[10:11]
	s_mov_b32 m0, s34
	ds_read_b128 v[192:195], v163 offset:49152
	ds_read_b128 v[196:199], v163 offset:50176
	ds_read_b128 v[200:203], v163 offset:51200
	ds_read_b128 v[204:207], v163 offset:52224
	ds_read_b128 v[208:211], v163 offset:53248
	ds_read_b128 v[212:215], v163 offset:54272
	ds_read_b128 v[216:219], v163 offset:55296
	ds_read_b128 v[220:223], v163 offset:56320
	global_load_lds_dwordx4 v[224:225], off
	s_add_i32 m0, s34, 0x2000
	s_add_u32 s30, s30, 0x40080
	v_lshl_add_u64 v[224:225], v[226:227], 0, s[10:11]
	s_addc_u32 s31, s31, 0
	s_add_i32 s34, s51, s54
	global_load_lds_dwordx4 v[224:225], off
	v_lshl_add_u64 v[224:225], s[30:31], 0, v[134:135]
	s_mov_b32 m0, s34
	s_nop 0
	global_load_lds_dwordx4 v[224:225], off
	v_lshl_add_u64 v[224:225], s[30:31], 0, v[130:131]
	s_add_i32 m0, s34, 0x2000
	s_nop 0
	global_load_lds_dwordx4 v[224:225], off
	v_lshl_add_u64 v[224:225], v[228:229], 0, s[10:11]
	s_mov_b32 m0, s65
	s_nop 0
	global_load_lds_dwordx4 v[224:225], off
	v_lshl_add_u64 v[224:225], v[230:231], 0, s[10:11]
	s_mov_b32 m0, s66
	s_nop 0
	global_load_lds_dwordx4 v[224:225], off
	s_waitcnt vmcnt(8)
	s_waitcnt lgkmcnt(0)
	s_barrier
	v_mfma_f32_16x16x32_bf16 v[110:113], v[154:157], v[192:195], v[110:113]
	v_mfma_f32_16x16x32_bf16 v[110:113], v[164:167], v[196:199], v[110:113]
	v_mfma_f32_16x16x32_bf16 v[86:89], v[168:171], v[192:195], v[86:89]
	v_mfma_f32_16x16x32_bf16 v[86:89], v[172:175], v[196:199], v[86:89]
	v_mfma_f32_16x16x32_bf16 v[106:109], v[154:157], v[200:203], v[106:109]
	v_mfma_f32_16x16x32_bf16 v[106:109], v[164:167], v[204:207], v[106:109]
	v_mfma_f32_16x16x32_bf16 v[82:85], v[168:171], v[200:203], v[82:85]
	v_mfma_f32_16x16x32_bf16 v[82:85], v[172:175], v[204:207], v[82:85]
	v_mfma_f32_16x16x32_bf16 v[118:121], v[154:157], v[208:211], v[118:121]
	v_mfma_f32_16x16x32_bf16 v[118:121], v[164:167], v[212:215], v[118:121]
	v_mfma_f32_16x16x32_bf16 v[94:97], v[168:171], v[208:211], v[94:97]
	v_mfma_f32_16x16x32_bf16 v[94:97], v[172:175], v[212:215], v[94:97]
	v_mfma_f32_16x16x32_bf16 v[126:129], v[154:157], v[216:219], v[126:129]
	v_mfma_f32_16x16x32_bf16 v[126:129], v[164:167], v[220:223], v[126:129]
	v_mfma_f32_16x16x32_bf16 v[102:105], v[168:171], v[216:219], v[102:105]
	v_mfma_f32_16x16x32_bf16 v[102:105], v[172:175], v[220:223], v[102:105]
	v_mfma_f32_16x16x32_bf16 v[70:73], v[176:179], v[192:195], v[70:73]
	v_mfma_f32_16x16x32_bf16 v[70:73], v[180:183], v[196:199], v[70:73]
	v_mfma_f32_16x16x32_bf16 v[58:61], v[184:187], v[192:195], v[58:61]
	v_mfma_f32_16x16x32_bf16 v[58:61], v[188:191], v[196:199], v[58:61]
	v_mfma_f32_16x16x32_bf16 v[74:77], v[176:179], v[200:203], v[74:77]
	v_mfma_f32_16x16x32_bf16 v[74:77], v[180:183], v[204:207], v[74:77]
	v_mfma_f32_16x16x32_bf16 v[78:81], v[184:187], v[200:203], v[78:81]
	v_mfma_f32_16x16x32_bf16 v[78:81], v[188:191], v[204:207], v[78:81]
	v_mfma_f32_16x16x32_bf16 v[114:117], v[176:179], v[208:211], v[114:117]
	v_mfma_f32_16x16x32_bf16 v[114:117], v[180:183], v[212:215], v[114:117]
	v_mfma_f32_16x16x32_bf16 v[90:93], v[184:187], v[208:211], v[90:93]
	v_mfma_f32_16x16x32_bf16 v[90:93], v[188:191], v[212:215], v[90:93]
	v_mfma_f32_16x16x32_bf16 v[122:125], v[176:179], v[216:219], v[122:125]
	v_mfma_f32_16x16x32_bf16 v[122:125], v[180:183], v[220:223], v[122:125]
	v_mfma_f32_16x16x32_bf16 v[98:101], v[184:187], v[216:219], v[98:101]
	v_mfma_f32_16x16x32_bf16 v[98:101], v[188:191], v[220:223], v[98:101]
	s_barrier
	s_add_u32 s28, s28, 0x100
	s_addc_u32 s29, s29, 0
	s_add_u32 s17, s17, 0x100
	s_addc_u32 s19, s19, 0
	s_cmp_ge_i32 s75, s62
	s_mov_b32 s30, s75
	s_cbranch_scc0 .LBB0_256

.LBB0_351:
	v_add_u32_e32 v81, s62, v78
	s_waitcnt lgkmcnt(0)
	ds_read_b128 v[82:85], v81
	ds_read_b128 v[86:89], v81 offset:1024
	ds_read_b128 v[90:93], v81 offset:2048
	ds_read_b128 v[94:97], v81 offset:3072
	s_add_i32 s72, s24, 2
	s_add_u32 s22, s20, 0x100
	s_addc_u32 s23, s21, 0
	s_cmp_eq_u32 s61, s24
	s_cselect_b32 s24, s16, s70
	s_cselect_b32 s27, s15, s23
	s_cselect_b32 s26, s14, s22
	s_cselect_b32 s25, s17, s71
	s_mov_b32 m0, s63
	v_lshl_add_u64 v[130:131], s[20:21], 0, v[74:75]
	ds_read_b128 v[98:101], v79
	ds_read_b128 v[102:105], v79 offset:1024
	ds_read_b128 v[106:109], v79 offset:2048
	ds_read_b128 v[110:113], v79 offset:3072
	ds_read_b128 v[114:117], v79 offset:4096
	ds_read_b128 v[118:121], v79 offset:5120
	ds_read_b128 v[122:125], v79 offset:6144
	ds_read_b128 v[126:129], v79 offset:7168
	global_load_lds_dwordx4 v[130:131], off
	v_lshl_add_u64 v[130:131], s[20:21], 0, v[76:77]
	s_mov_b32 m0, s64
	s_nop 0
	global_load_lds_dwordx4 v[130:131], off
	s_waitcnt vmcnt(8)
	s_waitcnt lgkmcnt(0)
	s_barrier
	v_mfma_f32_16x16x32_bf16 v[62:65], v[82:85], v[98:101], v[62:65]
	v_mfma_f32_16x16x32_bf16 v[62:65], v[86:89], v[102:105], v[62:65]
	v_mfma_f32_16x16x32_bf16 v[58:61], v[90:93], v[98:101], v[58:61]
	v_mfma_f32_16x16x32_bf16 v[58:61], v[94:97], v[102:105], v[58:61]
	v_mfma_f32_16x16x32_bf16 v[54:57], v[82:85], v[106:109], v[54:57]
	v_mfma_f32_16x16x32_bf16 v[54:57], v[86:89], v[110:113], v[54:57]
	v_mfma_f32_16x16x32_bf16 v[50:53], v[90:93], v[106:109], v[50:53]
	v_mfma_f32_16x16x32_bf16 v[50:53], v[94:97], v[110:113], v[50:53]
	v_mfma_f32_16x16x32_bf16 v[46:49], v[82:85], v[114:117], v[46:49]
	v_mfma_f32_16x16x32_bf16 v[46:49], v[86:89], v[118:121], v[46:49]
	v_mfma_f32_16x16x32_bf16 v[42:45], v[90:93], v[114:117], v[42:45]
	v_mfma_f32_16x16x32_bf16 v[42:45], v[94:97], v[118:121], v[42:45]
	v_mfma_f32_16x16x32_bf16 v[34:37], v[82:85], v[122:125], v[34:37]
	v_mfma_f32_16x16x32_bf16 v[34:37], v[86:89], v[126:129], v[34:37]
	v_mfma_f32_16x16x32_bf16 v[26:29], v[90:93], v[122:125], v[26:29]
	v_mfma_f32_16x16x32_bf16 v[26:29], v[94:97], v[126:129], v[26:29]
	s_barrier
	s_mov_b32 m0, s65
	v_lshl_add_u64 v[130:131], s[24:25], 0, v[70:71]
	s_add_u32 s20, s24, 0x10000
	ds_read_b128 v[98:101], v79 offset:16384
	ds_read_b128 v[102:105], v79 offset:17408
	ds_read_b128 v[106:109], v79 offset:18432
	ds_read_b128 v[110:113], v79 offset:19456
	ds_read_b128 v[114:117], v79 offset:20480
	ds_read_b128 v[118:121], v79 offset:21504
	ds_read_b128 v[122:125], v79 offset:22528
	ds_read_b128 v[126:129], v79 offset:23552
	global_load_lds_dwordx4 v[130:131], off
	v_lshl_add_u64 v[132:133], s[24:25], 0, v[66:67]
	s_mov_b32 m0, s66
	s_addc_u32 s21, s25, 0
	global_load_lds_dwordx4 v[132:133], off
	v_lshl_add_u64 v[134:135], s[20:21], 0, v[70:71]
	s_mov_b32 m0, s34
	v_lshl_add_u64 v[136:137], s[26:27], 0, v[68:69]
	global_load_lds_dwordx4 v[134:135], off
	v_lshl_add_u64 v[134:135], s[20:21], 0, v[66:67]
	s_mov_b32 m0, s35
	s_nop 0
	global_load_lds_dwordx4 v[134:135], off
	v_lshl_add_u64 v[134:135], s[26:27], 0, v[72:73]
	s_mov_b32 m0, s31
	s_nop 0
	global_load_lds_dwordx4 v[134:135], off
	s_mov_b32 m0, s52
	s_nop 0
	global_load_lds_dwordx4 v[136:137], off
	s_waitcnt vmcnt(8)
	s_waitcnt lgkmcnt(0)
	s_barrier
	v_mfma_f32_16x16x32_bf16 v[38:41], v[82:85], v[98:101], v[38:41]
	v_mfma_f32_16x16x32_bf16 v[38:41], v[86:89], v[102:105], v[38:41]
	v_mfma_f32_16x16x32_bf16 v[30:33], v[90:93], v[98:101], v[30:33]
	v_mfma_f32_16x16x32_bf16 v[30:33], v[94:97], v[102:105], v[30:33]
	v_mfma_f32_16x16x32_bf16 v[22:25], v[82:85], v[106:109], v[22:25]
	v_mfma_f32_16x16x32_bf16 v[22:25], v[86:89], v[110:113], v[22:25]
	v_mfma_f32_16x16x32_bf16 v[18:21], v[90:93], v[106:109], v[18:21]
	v_mfma_f32_16x16x32_bf16 v[18:21], v[94:97], v[110:113], v[18:21]
	v_mfma_f32_16x16x32_bf16 v[14:17], v[82:85], v[114:117], v[14:17]
	v_mfma_f32_16x16x32_bf16 v[14:17], v[86:89], v[118:121], v[14:17]
	v_mfma_f32_16x16x32_bf16 v[10:13], v[90:93], v[114:117], v[10:13]
	v_mfma_f32_16x16x32_bf16 v[10:13], v[94:97], v[118:121], v[10:13]
	v_mfma_f32_16x16x32_bf16 v[6:9], v[82:85], v[122:125], v[6:9]
	v_mfma_f32_16x16x32_bf16 v[6:9], v[86:89], v[126:129], v[6:9]
	v_mfma_f32_16x16x32_bf16 v[2:5], v[90:93], v[122:125], v[2:5]
	v_mfma_f32_16x16x32_bf16 v[2:5], v[94:97], v[126:129], v[2:5]
	s_barrier
	v_add_u32_e32 v81, s67, v78
	ds_read_b128 v[82:85], v81
	ds_read_b128 v[86:89], v81 offset:1024
	ds_read_b128 v[90:93], v81 offset:2048
	ds_read_b128 v[94:97], v81 offset:3072
	s_add_u32 s20, s26, 0x18000
	s_addc_u32 s21, s27, 0
	s_mov_b32 m0, s53
	v_lshl_add_u64 v[138:139], s[20:21], 0, v[72:73]
	ds_read_b128 v[98:101], v79 offset:32768
	ds_read_b128 v[102:105], v79 offset:33792
	ds_read_b128 v[106:109], v79 offset:34816
	ds_read_b128 v[110:113], v79 offset:35840
	ds_read_b128 v[114:117], v79 offset:36864
	ds_read_b128 v[118:121], v79 offset:37888
	ds_read_b128 v[122:125], v79 offset:38912
	ds_read_b128 v[126:129], v79 offset:39936
	global_load_lds_dwordx4 v[138:139], off
	v_lshl_add_u64 v[138:139], s[20:21], 0, v[68:69]
	s_mov_b32 m0, s54
	s_nop 0
	global_load_lds_dwordx4 v[138:139], off
	s_waitcnt vmcnt(8)
	s_waitcnt lgkmcnt(0)
	s_barrier
	v_mfma_f32_16x16x32_bf16 v[62:65], v[82:85], v[98:101], v[62:65]
	v_mfma_f32_16x16x32_bf16 v[62:65], v[86:89], v[102:105], v[62:65]
	v_mfma_f32_16x16x32_bf16 v[58:61], v[90:93], v[98:101], v[58:61]
	v_mfma_f32_16x16x32_bf16 v[58:61], v[94:97], v[102:105], v[58:61]
	v_mfma_f32_16x16x32_bf16 v[54:57], v[82:85], v[106:109], v[54:57]
	v_mfma_f32_16x16x32_bf16 v[54:57], v[86:89], v[110:113], v[54:57]
	v_mfma_f32_16x16x32_bf16 v[50:53], v[90:93], v[106:109], v[50:53]
	v_mfma_f32_16x16x32_bf16 v[50:53], v[94:97], v[110:113], v[50:53]
	v_mfma_f32_16x16x32_bf16 v[46:49], v[82:85], v[114:117], v[46:49]
	v_mfma_f32_16x16x32_bf16 v[46:49], v[86:89], v[118:121], v[46:49]
	v_mfma_f32_16x16x32_bf16 v[42:45], v[90:93], v[114:117], v[42:45]
	v_mfma_f32_16x16x32_bf16 v[42:45], v[94:97], v[118:121], v[42:45]
	v_mfma_f32_16x16x32_bf16 v[34:37], v[82:85], v[122:125], v[34:37]
	v_mfma_f32_16x16x32_bf16 v[34:37], v[86:89], v[126:129], v[34:37]
	v_mfma_f32_16x16x32_bf16 v[26:29], v[90:93], v[122:125], v[26:29]
	v_mfma_f32_16x16x32_bf16 v[26:29], v[94:97], v[126:129], v[26:29]
	s_barrier
	s_mov_b32 m0, s68
	v_lshl_add_u64 v[130:131], v[130:131], 0, s[6:7]
	s_add_u32 s20, s24, 0x10080
	ds_read_b128 v[98:101], v79 offset:49152
	ds_read_b128 v[102:105], v79 offset:50176
	ds_read_b128 v[106:109], v79 offset:51200
	ds_read_b128 v[110:113], v79 offset:52224
	ds_read_b128 v[114:117], v79 offset:53248
	ds_read_b128 v[118:121], v79 offset:54272
	ds_read_b128 v[122:125], v79 offset:55296
	ds_read_b128 v[126:129], v79 offset:56320
	global_load_lds_dwordx4 v[130:131], off
	v_lshl_add_u64 v[130:131], v[132:133], 0, s[6:7]
	s_mov_b32 m0, s69
	s_addc_u32 s21, s25, 0
	global_load_lds_dwordx4 v[130:131], off
	v_lshl_add_u64 v[130:131], s[20:21], 0, v[70:71]
	s_mov_b32 m0, s59
	s_nop 0
	global_load_lds_dwordx4 v[130:131], off
	v_lshl_add_u64 v[130:131], s[20:21], 0, v[66:67]
	s_mov_b32 m0, s60
	s_nop 0
	global_load_lds_dwordx4 v[130:131], off
	v_lshl_add_u64 v[130:131], v[134:135], 0, s[6:7]
	s_mov_b32 m0, s57
	s_nop 0
	global_load_lds_dwordx4 v[130:131], off
	v_lshl_add_u64 v[130:131], v[136:137], 0, s[6:7]
	s_mov_b32 m0, s58
	s_nop 0
	global_load_lds_dwordx4 v[130:131], off
	s_waitcnt vmcnt(8)
	s_waitcnt lgkmcnt(0)
	s_barrier
	v_mfma_f32_16x16x32_bf16 v[38:41], v[82:85], v[98:101], v[38:41]
	v_mfma_f32_16x16x32_bf16 v[38:41], v[86:89], v[102:105], v[38:41]
	v_mfma_f32_16x16x32_bf16 v[30:33], v[90:93], v[98:101], v[30:33]
	v_mfma_f32_16x16x32_bf16 v[30:33], v[94:97], v[102:105], v[30:33]
	v_mfma_f32_16x16x32_bf16 v[22:25], v[82:85], v[106:109], v[22:25]
	v_mfma_f32_16x16x32_bf16 v[22:25], v[86:89], v[110:113], v[22:25]
	v_mfma_f32_16x16x32_bf16 v[18:21], v[90:93], v[106:109], v[18:21]
	v_mfma_f32_16x16x32_bf16 v[18:21], v[94:97], v[110:113], v[18:21]
	v_mfma_f32_16x16x32_bf16 v[14:17], v[82:85], v[114:117], v[14:17]
	v_mfma_f32_16x16x32_bf16 v[14:17], v[86:89], v[118:121], v[14:17]
	v_mfma_f32_16x16x32_bf16 v[10:13], v[90:93], v[114:117], v[10:13]
	v_mfma_f32_16x16x32_bf16 v[10:13], v[94:97], v[118:121], v[10:13]
	v_mfma_f32_16x16x32_bf16 v[6:9], v[82:85], v[122:125], v[6:9]
	v_mfma_f32_16x16x32_bf16 v[6:9], v[86:89], v[126:129], v[6:9]
	v_mfma_f32_16x16x32_bf16 v[2:5], v[90:93], v[122:125], v[2:5]
	v_mfma_f32_16x16x32_bf16 v[2:5], v[94:97], v[126:129], v[2:5]
	s_barrier
	s_add_u32 s70, s70, 0x100
	s_addc_u32 s71, s71, 0
	s_cmp_ge_i32 s72, s56
	s_mov_b64 s[20:21], s[22:23]
	s_mov_b32 s24, s72
	s_cbranch_scc0 .LBB0_351

.LBB0_468:
	v_add_u32_e32 v144, s62, v1
	ds_read_b128 v[150:153], v144
	ds_read_b128 v[154:157], v144 offset:1024
	ds_read_b128 v[158:161], v144 offset:2048
	ds_read_b128 v[162:165], v144 offset:3072
	v_add_u32_e32 v144, s63, v1
	ds_read_b128 v[166:169], v144
	ds_read_b128 v[170:173], v144 offset:1024
	ds_read_b128 v[174:177], v144 offset:2048
	ds_read_b128 v[178:181], v144 offset:3072
	s_add_i32 s77, s26, 2
	s_add_u32 s24, s22, 0x100
	s_addc_u32 s25, s23, 0
	s_cmp_eq_u32 s61, s26
	s_cselect_b32 s26, s16, s75
	s_cselect_b32 s29, s15, s25
	s_cselect_b32 s28, s14, s24
	s_cselect_b32 s27, s17, s76
	s_mov_b32 m0, s64
	v_lshl_add_u64 v[144:145], s[22:23], 0, v[140:141]
	ds_read_b128 v[182:185], v149
	ds_read_b128 v[186:189], v149 offset:1024
	ds_read_b128 v[190:193], v149 offset:2048
	ds_read_b128 v[194:197], v149 offset:3072
	ds_read_b128 v[198:201], v149 offset:4096
	ds_read_b128 v[202:205], v149 offset:5120
	ds_read_b128 v[206:209], v149 offset:6144
	ds_read_b128 v[210:213], v149 offset:7168
	global_load_lds_dwordx4 v[144:145], off
	v_lshl_add_u64 v[144:145], s[22:23], 0, v[142:143]
	s_mov_b32 m0, s65
	s_nop 0
	global_load_lds_dwordx4 v[144:145], off
	s_waitcnt vmcnt(8)
	s_waitcnt lgkmcnt(0)
	s_barrier
	v_mfma_f32_16x16x32_bf16 v[126:129], v[150:153], v[182:185], v[126:129]
	v_mfma_f32_16x16x32_bf16 v[126:129], v[154:157], v[186:189], v[126:129]
	v_mfma_f32_16x16x32_bf16 v[122:125], v[158:161], v[182:185], v[122:125]
	v_mfma_f32_16x16x32_bf16 v[122:125], v[162:165], v[186:189], v[122:125]
	v_mfma_f32_16x16x32_bf16 v[110:113], v[150:153], v[190:193], v[110:113]
	v_mfma_f32_16x16x32_bf16 v[110:113], v[154:157], v[194:197], v[110:113]
	v_mfma_f32_16x16x32_bf16 v[106:109], v[158:161], v[190:193], v[106:109]
	v_mfma_f32_16x16x32_bf16 v[106:109], v[162:165], v[194:197], v[106:109]
	v_mfma_f32_16x16x32_bf16 v[94:97], v[150:153], v[198:201], v[94:97]
	v_mfma_f32_16x16x32_bf16 v[94:97], v[154:157], v[202:205], v[94:97]
	v_mfma_f32_16x16x32_bf16 v[90:93], v[158:161], v[198:201], v[90:93]
	v_mfma_f32_16x16x32_bf16 v[90:93], v[162:165], v[202:205], v[90:93]
	v_mfma_f32_16x16x32_bf16 v[78:81], v[150:153], v[206:209], v[78:81]
	v_mfma_f32_16x16x32_bf16 v[78:81], v[154:157], v[210:213], v[78:81]
	v_mfma_f32_16x16x32_bf16 v[74:77], v[158:161], v[206:209], v[74:77]
	v_mfma_f32_16x16x32_bf16 v[74:77], v[162:165], v[210:213], v[74:77]
	v_mfma_f32_16x16x32_bf16 v[118:121], v[166:169], v[182:185], v[118:121]
	v_mfma_f32_16x16x32_bf16 v[118:121], v[170:173], v[186:189], v[118:121]
	v_mfma_f32_16x16x32_bf16 v[114:117], v[174:177], v[182:185], v[114:117]
	v_mfma_f32_16x16x32_bf16 v[114:117], v[178:181], v[186:189], v[114:117]
	v_mfma_f32_16x16x32_bf16 v[102:105], v[166:169], v[190:193], v[102:105]
	v_mfma_f32_16x16x32_bf16 v[102:105], v[170:173], v[194:197], v[102:105]
	v_mfma_f32_16x16x32_bf16 v[98:101], v[174:177], v[190:193], v[98:101]
	v_mfma_f32_16x16x32_bf16 v[98:101], v[178:181], v[194:197], v[98:101]
	v_mfma_f32_16x16x32_bf16 v[86:89], v[166:169], v[198:201], v[86:89]
	v_mfma_f32_16x16x32_bf16 v[86:89], v[170:173], v[202:205], v[86:89]
	v_mfma_f32_16x16x32_bf16 v[82:85], v[174:177], v[198:201], v[82:85]
	v_mfma_f32_16x16x32_bf16 v[82:85], v[178:181], v[202:205], v[82:85]
	v_mfma_f32_16x16x32_bf16 v[70:73], v[166:169], v[206:209], v[70:73]
	v_mfma_f32_16x16x32_bf16 v[70:73], v[170:173], v[210:213], v[70:73]
	v_mfma_f32_16x16x32_bf16 v[66:69], v[174:177], v[206:209], v[66:69]
	v_mfma_f32_16x16x32_bf16 v[66:69], v[178:181], v[210:213], v[66:69]
	s_barrier
	s_mov_b32 m0, s66
	v_lshl_add_u64 v[144:145], s[26:27], 0, v[134:135]
	s_add_u32 s22, s26, 0x18000
	ds_read_b128 v[182:185], v149 offset:16384
	ds_read_b128 v[186:189], v149 offset:17408
	ds_read_b128 v[190:193], v149 offset:18432
	ds_read_b128 v[194:197], v149 offset:19456
	ds_read_b128 v[198:201], v149 offset:20480
	ds_read_b128 v[202:205], v149 offset:21504
	ds_read_b128 v[206:209], v149 offset:22528
	ds_read_b128 v[210:213], v149 offset:23552
	global_load_lds_dwordx4 v[144:145], off
	v_lshl_add_u64 v[214:215], s[26:27], 0, v[130:131]
	s_mov_b32 m0, s67
	s_addc_u32 s23, s27, 0
	global_load_lds_dwordx4 v[214:215], off
	v_lshl_add_u64 v[216:217], s[22:23], 0, v[134:135]
	s_mov_b32 m0, s68
	v_lshl_add_u64 v[218:219], s[28:29], 0, v[132:133]
	global_load_lds_dwordx4 v[216:217], off
	v_lshl_add_u64 v[216:217], s[22:23], 0, v[130:131]
	s_mov_b32 m0, s69
	s_nop 0
	global_load_lds_dwordx4 v[216:217], off
	v_lshl_add_u64 v[216:217], s[28:29], 0, v[136:137]
	s_mov_b32 m0, s34
	s_nop 0
	global_load_lds_dwordx4 v[216:217], off
	s_mov_b32 m0, s35
	s_nop 0
	global_load_lds_dwordx4 v[218:219], off
	s_waitcnt vmcnt(8)
	s_waitcnt lgkmcnt(0)
	s_barrier
	v_mfma_f32_16x16x32_bf16 v[62:65], v[150:153], v[182:185], v[62:65]
	v_mfma_f32_16x16x32_bf16 v[62:65], v[154:157], v[186:189], v[62:65]
	v_mfma_f32_16x16x32_bf16 v[58:61], v[158:161], v[182:185], v[58:61]
	v_mfma_f32_16x16x32_bf16 v[58:61], v[162:165], v[186:189], v[58:61]
	v_mfma_f32_16x16x32_bf16 v[46:49], v[150:153], v[190:193], v[46:49]
	v_mfma_f32_16x16x32_bf16 v[46:49], v[154:157], v[194:197], v[46:49]
	v_mfma_f32_16x16x32_bf16 v[42:45], v[158:161], v[190:193], v[42:45]
	v_mfma_f32_16x16x32_bf16 v[42:45], v[162:165], v[194:197], v[42:45]
	v_mfma_f32_16x16x32_bf16 v[30:33], v[150:153], v[198:201], v[30:33]
	v_mfma_f32_16x16x32_bf16 v[30:33], v[154:157], v[202:205], v[30:33]
	v_mfma_f32_16x16x32_bf16 v[26:29], v[158:161], v[198:201], v[26:29]
	v_mfma_f32_16x16x32_bf16 v[26:29], v[162:165], v[202:205], v[26:29]
	v_mfma_f32_16x16x32_bf16 v[14:17], v[150:153], v[206:209], v[14:17]
	v_mfma_f32_16x16x32_bf16 v[14:17], v[154:157], v[210:213], v[14:17]
	v_mfma_f32_16x16x32_bf16 v[10:13], v[158:161], v[206:209], v[10:13]
	v_mfma_f32_16x16x32_bf16 v[10:13], v[162:165], v[210:213], v[10:13]
	v_mfma_f32_16x16x32_bf16 v[54:57], v[166:169], v[182:185], v[54:57]
	v_mfma_f32_16x16x32_bf16 v[54:57], v[170:173], v[186:189], v[54:57]
	v_mfma_f32_16x16x32_bf16 v[50:53], v[174:177], v[182:185], v[50:53]
	v_mfma_f32_16x16x32_bf16 v[50:53], v[178:181], v[186:189], v[50:53]
	v_mfma_f32_16x16x32_bf16 v[38:41], v[166:169], v[190:193], v[38:41]
	v_mfma_f32_16x16x32_bf16 v[38:41], v[170:173], v[194:197], v[38:41]
	v_mfma_f32_16x16x32_bf16 v[34:37], v[174:177], v[190:193], v[34:37]
	v_mfma_f32_16x16x32_bf16 v[34:37], v[178:181], v[194:197], v[34:37]
	v_mfma_f32_16x16x32_bf16 v[22:25], v[166:169], v[198:201], v[22:25]
	v_mfma_f32_16x16x32_bf16 v[22:25], v[170:173], v[202:205], v[22:25]
	v_mfma_f32_16x16x32_bf16 v[18:21], v[174:177], v[198:201], v[18:21]
	v_mfma_f32_16x16x32_bf16 v[18:21], v[178:181], v[202:205], v[18:21]
	v_mfma_f32_16x16x32_bf16 v[6:9], v[166:169], v[206:209], v[6:9]
	v_mfma_f32_16x16x32_bf16 v[6:9], v[170:173], v[210:213], v[6:9]
	v_mfma_f32_16x16x32_bf16 v[2:5], v[174:177], v[206:209], v[2:5]
	v_mfma_f32_16x16x32_bf16 v[2:5], v[178:181], v[210:213], v[2:5]
	s_barrier
	v_add_u32_e32 v162, s70, v1
	v_add_u32_e32 v178, s71, v1
	ds_read_b128 v[150:153], v162
	ds_read_b128 v[154:157], v162 offset:1024
	ds_read_b128 v[158:161], v162 offset:2048
	ds_read_b128 v[162:165], v162 offset:3072
	ds_read_b128 v[166:169], v178
	ds_read_b128 v[170:173], v178 offset:1024
	ds_read_b128 v[174:177], v178 offset:2048
	ds_read_b128 v[178:181], v178 offset:3072
	s_add_u32 s22, s28, 0x18000
	s_addc_u32 s23, s29, 0
	s_mov_b32 m0, s52
	v_lshl_add_u64 v[220:221], s[22:23], 0, v[136:137]
	ds_read_b128 v[182:185], v149 offset:32768
	ds_read_b128 v[186:189], v149 offset:33792
	ds_read_b128 v[190:193], v149 offset:34816
	ds_read_b128 v[194:197], v149 offset:35840
	ds_read_b128 v[198:201], v149 offset:36864
	ds_read_b128 v[202:205], v149 offset:37888
	ds_read_b128 v[206:209], v149 offset:38912
	ds_read_b128 v[210:213], v149 offset:39936
	global_load_lds_dwordx4 v[220:221], off
	v_lshl_add_u64 v[220:221], s[22:23], 0, v[132:133]
	s_mov_b32 m0, s53
	s_nop 0
	global_load_lds_dwordx4 v[220:221], off
	s_waitcnt vmcnt(8)
	s_waitcnt lgkmcnt(0)
	s_barrier
	v_mfma_f32_16x16x32_bf16 v[126:129], v[150:153], v[182:185], v[126:129]
	v_mfma_f32_16x16x32_bf16 v[126:129], v[154:157], v[186:189], v[126:129]
	v_mfma_f32_16x16x32_bf16 v[122:125], v[158:161], v[182:185], v[122:125]
	v_mfma_f32_16x16x32_bf16 v[122:125], v[162:165], v[186:189], v[122:125]
	v_mfma_f32_16x16x32_bf16 v[110:113], v[150:153], v[190:193], v[110:113]
	v_mfma_f32_16x16x32_bf16 v[110:113], v[154:157], v[194:197], v[110:113]
	v_mfma_f32_16x16x32_bf16 v[106:109], v[158:161], v[190:193], v[106:109]
	v_mfma_f32_16x16x32_bf16 v[106:109], v[162:165], v[194:197], v[106:109]
	v_mfma_f32_16x16x32_bf16 v[94:97], v[150:153], v[198:201], v[94:97]
	v_mfma_f32_16x16x32_bf16 v[94:97], v[154:157], v[202:205], v[94:97]
	v_mfma_f32_16x16x32_bf16 v[90:93], v[158:161], v[198:201], v[90:93]
	v_mfma_f32_16x16x32_bf16 v[90:93], v[162:165], v[202:205], v[90:93]
	v_mfma_f32_16x16x32_bf16 v[78:81], v[150:153], v[206:209], v[78:81]
	v_mfma_f32_16x16x32_bf16 v[78:81], v[154:157], v[210:213], v[78:81]
	v_mfma_f32_16x16x32_bf16 v[74:77], v[158:161], v[206:209], v[74:77]
	v_mfma_f32_16x16x32_bf16 v[74:77], v[162:165], v[210:213], v[74:77]
	v_mfma_f32_16x16x32_bf16 v[118:121], v[166:169], v[182:185], v[118:121]
	v_mfma_f32_16x16x32_bf16 v[118:121], v[170:173], v[186:189], v[118:121]
	v_mfma_f32_16x16x32_bf16 v[114:117], v[174:177], v[182:185], v[114:117]
	v_mfma_f32_16x16x32_bf16 v[114:117], v[178:181], v[186:189], v[114:117]
	v_mfma_f32_16x16x32_bf16 v[102:105], v[166:169], v[190:193], v[102:105]
	v_mfma_f32_16x16x32_bf16 v[102:105], v[170:173], v[194:197], v[102:105]
	v_mfma_f32_16x16x32_bf16 v[98:101], v[174:177], v[190:193], v[98:101]
	v_mfma_f32_16x16x32_bf16 v[98:101], v[178:181], v[194:197], v[98:101]
	v_mfma_f32_16x16x32_bf16 v[86:89], v[166:169], v[198:201], v[86:89]
	v_mfma_f32_16x16x32_bf16 v[86:89], v[170:173], v[202:205], v[86:89]
	v_mfma_f32_16x16x32_bf16 v[82:85], v[174:177], v[198:201], v[82:85]
	v_mfma_f32_16x16x32_bf16 v[82:85], v[178:181], v[202:205], v[82:85]
	v_mfma_f32_16x16x32_bf16 v[70:73], v[166:169], v[206:209], v[70:73]
	v_mfma_f32_16x16x32_bf16 v[70:73], v[170:173], v[210:213], v[70:73]
	v_mfma_f32_16x16x32_bf16 v[66:69], v[174:177], v[206:209], v[66:69]
	v_mfma_f32_16x16x32_bf16 v[66:69], v[178:181], v[210:213], v[66:69]
	s_barrier
	s_mov_b32 m0, s72
	v_lshl_add_u64 v[144:145], v[144:145], 0, s[4:5]
	ds_read_b128 v[182:185], v149 offset:49152
	ds_read_b128 v[186:189], v149 offset:50176
	ds_read_b128 v[190:193], v149 offset:51200
	ds_read_b128 v[194:197], v149 offset:52224
	ds_read_b128 v[198:201], v149 offset:53248
	ds_read_b128 v[202:205], v149 offset:54272
	ds_read_b128 v[206:209], v149 offset:55296
	ds_read_b128 v[210:213], v149 offset:56320
	global_load_lds_dwordx4 v[144:145], off
	s_add_i32 m0, s72, 0x2000
	s_add_u32 s22, s26, 0x18080
	v_lshl_add_u64 v[144:145], v[214:215], 0, s[4:5]
	s_addc_u32 s23, s27, 0
	s_add_i32 s26, s71, s30
	global_load_lds_dwordx4 v[144:145], off
	v_lshl_add_u64 v[144:145], s[22:23], 0, v[134:135]
	s_mov_b32 m0, s26
	s_nop 0
	global_load_lds_dwordx4 v[144:145], off
	v_lshl_add_u64 v[144:145], s[22:23], 0, v[130:131]
	s_add_i32 m0, s26, 0x2000
	s_nop 0
	global_load_lds_dwordx4 v[144:145], off
	v_lshl_add_u64 v[144:145], v[216:217], 0, s[4:5]
	s_mov_b32 m0, s59
	s_nop 0
	global_load_lds_dwordx4 v[144:145], off
	v_lshl_add_u64 v[144:145], v[218:219], 0, s[4:5]
	s_mov_b32 m0, s60
	s_nop 0
	global_load_lds_dwordx4 v[144:145], off
	s_waitcnt vmcnt(8)
	s_waitcnt lgkmcnt(0)
	s_barrier
	v_mfma_f32_16x16x32_bf16 v[62:65], v[150:153], v[182:185], v[62:65]
	v_mfma_f32_16x16x32_bf16 v[62:65], v[154:157], v[186:189], v[62:65]
	v_mfma_f32_16x16x32_bf16 v[58:61], v[158:161], v[182:185], v[58:61]
	v_mfma_f32_16x16x32_bf16 v[58:61], v[162:165], v[186:189], v[58:61]
	v_mfma_f32_16x16x32_bf16 v[46:49], v[150:153], v[190:193], v[46:49]
	v_mfma_f32_16x16x32_bf16 v[46:49], v[154:157], v[194:197], v[46:49]
	v_mfma_f32_16x16x32_bf16 v[42:45], v[158:161], v[190:193], v[42:45]
	v_mfma_f32_16x16x32_bf16 v[42:45], v[162:165], v[194:197], v[42:45]
	v_mfma_f32_16x16x32_bf16 v[30:33], v[150:153], v[198:201], v[30:33]
	v_mfma_f32_16x16x32_bf16 v[30:33], v[154:157], v[202:205], v[30:33]
	v_mfma_f32_16x16x32_bf16 v[26:29], v[158:161], v[198:201], v[26:29]
	v_mfma_f32_16x16x32_bf16 v[26:29], v[162:165], v[202:205], v[26:29]
	v_mfma_f32_16x16x32_bf16 v[14:17], v[150:153], v[206:209], v[14:17]
	v_mfma_f32_16x16x32_bf16 v[14:17], v[154:157], v[210:213], v[14:17]
	v_mfma_f32_16x16x32_bf16 v[10:13], v[158:161], v[206:209], v[10:13]
	v_mfma_f32_16x16x32_bf16 v[10:13], v[162:165], v[210:213], v[10:13]
	v_mfma_f32_16x16x32_bf16 v[54:57], v[166:169], v[182:185], v[54:57]
	v_mfma_f32_16x16x32_bf16 v[54:57], v[170:173], v[186:189], v[54:57]
	v_mfma_f32_16x16x32_bf16 v[50:53], v[174:177], v[182:185], v[50:53]
	v_mfma_f32_16x16x32_bf16 v[50:53], v[178:181], v[186:189], v[50:53]
	v_mfma_f32_16x16x32_bf16 v[38:41], v[166:169], v[190:193], v[38:41]
	v_mfma_f32_16x16x32_bf16 v[38:41], v[170:173], v[194:197], v[38:41]
	v_mfma_f32_16x16x32_bf16 v[34:37], v[174:177], v[190:193], v[34:37]
	v_mfma_f32_16x16x32_bf16 v[34:37], v[178:181], v[194:197], v[34:37]
	v_mfma_f32_16x16x32_bf16 v[22:25], v[166:169], v[198:201], v[22:25]
	v_mfma_f32_16x16x32_bf16 v[22:25], v[170:173], v[202:205], v[22:25]
	v_mfma_f32_16x16x32_bf16 v[18:21], v[174:177], v[198:201], v[18:21]
	v_mfma_f32_16x16x32_bf16 v[18:21], v[178:181], v[202:205], v[18:21]
	v_mfma_f32_16x16x32_bf16 v[6:9], v[166:169], v[206:209], v[6:9]
	v_mfma_f32_16x16x32_bf16 v[6:9], v[170:173], v[210:213], v[6:9]
	v_mfma_f32_16x16x32_bf16 v[2:5], v[174:177], v[206:209], v[2:5]
	v_mfma_f32_16x16x32_bf16 v[2:5], v[178:181], v[210:213], v[2:5]
	s_barrier
	s_add_u32 s75, s75, 0x100
	s_addc_u32 s76, s76, 0
	s_cmp_ge_i32 s77, s57
	s_mov_b64 s[22:23], s[24:25]
	s_mov_b32 s26, s77
	s_cbranch_scc0 .LBB0_468

.LBB0_599:
	v_add_u32_e32 v142, s74, v199
	v_add_u32_e32 v162, s75, v199
	ds_read_b128 v[130:133], v142
	ds_read_b128 v[134:137], v142 offset:1024
	ds_read_b128 v[138:141], v142 offset:2048
	ds_read_b128 v[142:145], v142 offset:3072
	ds_read_b128 v[146:149], v162
	ds_read_b128 v[150:153], v162 offset:1024
	ds_read_b128 v[174:177], v162 offset:2048
	ds_read_b128 v[178:181], v162 offset:3072
	s_add_i32 s31, s52, 2
	s_add_u32 s50, s34, 0x3ff000
	s_addc_u32 s51, s35, 0
	s_cmp_eq_u32 s71, s52
	s_cselect_b32 s56, s26, s50
	s_cselect_b32 s57, s27, s51
	s_cselect_b32 s54, s28, s23
	s_cselect_b32 s55, s29, s25
	s_add_u32 s52, s56, 0x400000
	s_addc_u32 s53, s57, 0
	v_lshl_add_u64 v[218:219], s[34:35], 0, v[164:165]
	s_add_i32 m0, s59, 0xc000
	ds_read_b128 v[182:185], v200
	ds_read_b128 v[186:189], v200 offset:1024
	ds_read_b128 v[190:193], v200 offset:2048
	ds_read_b128 v[194:197], v200 offset:3072
	ds_read_b128 v[202:205], v200 offset:4096
	ds_read_b128 v[206:209], v200 offset:5120
	ds_read_b128 v[210:213], v200 offset:6144
	ds_read_b128 v[214:217], v200 offset:7168
	global_load_lds_dwordx4 v[218:219], off
	v_lshl_add_u64 v[218:219], s[34:35], 0, v[166:167]
	s_add_i32 m0, s59, 0xe000
	s_nop 0
	global_load_lds_dwordx4 v[218:219], off
	s_waitcnt vmcnt(8)
	s_waitcnt lgkmcnt(0)
	s_barrier
	v_mfma_f32_16x16x32_bf16 v[118:121], v[130:133], v[182:185], v[118:121]
	v_mfma_f32_16x16x32_bf16 v[118:121], v[134:137], v[186:189], v[118:121]
	v_mfma_f32_16x16x32_bf16 v[122:125], v[138:141], v[182:185], v[122:125]
	v_mfma_f32_16x16x32_bf16 v[122:125], v[142:145], v[186:189], v[122:125]
	v_mfma_f32_16x16x32_bf16 v[110:113], v[130:133], v[190:193], v[110:113]
	v_mfma_f32_16x16x32_bf16 v[110:113], v[134:137], v[194:197], v[110:113]
	v_mfma_f32_16x16x32_bf16 v[106:109], v[138:141], v[190:193], v[106:109]
	v_mfma_f32_16x16x32_bf16 v[106:109], v[142:145], v[194:197], v[106:109]
	v_mfma_f32_16x16x32_bf16 v[94:97], v[130:133], v[202:205], v[94:97]
	v_mfma_f32_16x16x32_bf16 v[94:97], v[134:137], v[206:209], v[94:97]
	v_mfma_f32_16x16x32_bf16 v[90:93], v[138:141], v[202:205], v[90:93]
	v_mfma_f32_16x16x32_bf16 v[90:93], v[142:145], v[206:209], v[90:93]
	v_mfma_f32_16x16x32_bf16 v[78:81], v[130:133], v[210:213], v[78:81]
	v_mfma_f32_16x16x32_bf16 v[78:81], v[134:137], v[214:217], v[78:81]
	v_mfma_f32_16x16x32_bf16 v[74:77], v[138:141], v[210:213], v[74:77]
	v_mfma_f32_16x16x32_bf16 v[74:77], v[142:145], v[214:217], v[74:77]
	v_mfma_f32_16x16x32_bf16 v[126:129], v[146:149], v[182:185], v[126:129]
	v_mfma_f32_16x16x32_bf16 v[126:129], v[150:153], v[186:189], v[126:129]
	v_mfma_f32_16x16x32_bf16 v[114:117], v[174:177], v[182:185], v[114:117]
	v_mfma_f32_16x16x32_bf16 v[114:117], v[178:181], v[186:189], v[114:117]
	v_mfma_f32_16x16x32_bf16 v[102:105], v[146:149], v[190:193], v[102:105]
	v_mfma_f32_16x16x32_bf16 v[102:105], v[150:153], v[194:197], v[102:105]
	v_mfma_f32_16x16x32_bf16 v[98:101], v[174:177], v[190:193], v[98:101]
	v_mfma_f32_16x16x32_bf16 v[98:101], v[178:181], v[194:197], v[98:101]
	v_mfma_f32_16x16x32_bf16 v[86:89], v[146:149], v[202:205], v[86:89]
	v_mfma_f32_16x16x32_bf16 v[86:89], v[150:153], v[206:209], v[86:89]
	v_mfma_f32_16x16x32_bf16 v[82:85], v[174:177], v[202:205], v[82:85]
	v_mfma_f32_16x16x32_bf16 v[82:85], v[178:181], v[206:209], v[82:85]
	v_mfma_f32_16x16x32_bf16 v[70:73], v[146:149], v[210:213], v[70:73]
	v_mfma_f32_16x16x32_bf16 v[70:73], v[150:153], v[214:217], v[70:73]
	v_mfma_f32_16x16x32_bf16 v[66:69], v[174:177], v[210:213], v[66:69]
	v_mfma_f32_16x16x32_bf16 v[66:69], v[178:181], v[214:217], v[66:69]
	s_barrier
	s_add_i32 s50, s74, s41
	v_lshl_add_u64 v[218:219], s[54:55], 0, v[156:157]
	s_mov_b32 m0, s50
	ds_read_b128 v[182:185], v200 offset:16384
	ds_read_b128 v[186:189], v200 offset:17408
	ds_read_b128 v[190:193], v200 offset:18432
	ds_read_b128 v[194:197], v200 offset:19456
	ds_read_b128 v[202:205], v200 offset:20480
	ds_read_b128 v[206:209], v200 offset:21504
	ds_read_b128 v[210:213], v200 offset:22528
	ds_read_b128 v[214:217], v200 offset:23552
	global_load_lds_dwordx4 v[218:219], off
	s_add_i32 m0, s50, 0x2000
	s_add_u32 s50, s54, 0x20000
	v_lshl_add_u64 v[220:221], s[54:55], 0, v[160:161]
	s_addc_u32 s51, s55, 0
	s_add_i32 s78, s75, s41
	global_load_lds_dwordx4 v[220:221], off
	v_lshl_add_u64 v[222:223], s[50:51], 0, v[156:157]
	s_mov_b32 m0, s78
	s_nop 0
	global_load_lds_dwordx4 v[222:223], off
	v_lshl_add_u64 v[222:223], s[50:51], 0, v[160:161]
	s_add_i32 m0, s78, 0x2000
	s_nop 0
	global_load_lds_dwordx4 v[222:223], off
	v_lshl_add_u64 v[222:223], s[56:57], 0, v[154:155]
	s_mov_b32 m0, s59
	s_nop 0
	global_load_lds_dwordx4 v[222:223], off
	v_lshl_add_u64 v[222:223], s[56:57], 0, v[158:159]
	s_mov_b32 m0, s60
	s_nop 0
	global_load_lds_dwordx4 v[222:223], off
	s_waitcnt vmcnt(8)
	s_waitcnt lgkmcnt(0)
	s_barrier
	v_mfma_f32_16x16x32_bf16 v[62:65], v[130:133], v[182:185], v[62:65]
	v_mfma_f32_16x16x32_bf16 v[62:65], v[134:137], v[186:189], v[62:65]
	v_mfma_f32_16x16x32_bf16 v[58:61], v[138:141], v[182:185], v[58:61]
	v_mfma_f32_16x16x32_bf16 v[58:61], v[142:145], v[186:189], v[58:61]
	v_mfma_f32_16x16x32_bf16 v[46:49], v[130:133], v[190:193], v[46:49]
	v_mfma_f32_16x16x32_bf16 v[46:49], v[134:137], v[194:197], v[46:49]
	v_mfma_f32_16x16x32_bf16 v[42:45], v[138:141], v[190:193], v[42:45]
	v_mfma_f32_16x16x32_bf16 v[42:45], v[142:145], v[194:197], v[42:45]
	v_mfma_f32_16x16x32_bf16 v[30:33], v[130:133], v[202:205], v[30:33]
	v_mfma_f32_16x16x32_bf16 v[30:33], v[134:137], v[206:209], v[30:33]
	v_mfma_f32_16x16x32_bf16 v[26:29], v[138:141], v[202:205], v[26:29]
	v_mfma_f32_16x16x32_bf16 v[26:29], v[142:145], v[206:209], v[26:29]
	v_mfma_f32_16x16x32_bf16 v[14:17], v[130:133], v[210:213], v[14:17]
	v_mfma_f32_16x16x32_bf16 v[14:17], v[134:137], v[214:217], v[14:17]
	v_mfma_f32_16x16x32_bf16 v[10:13], v[138:141], v[210:213], v[10:13]
	v_mfma_f32_16x16x32_bf16 v[10:13], v[142:145], v[214:217], v[10:13]
	v_mfma_f32_16x16x32_bf16 v[54:57], v[146:149], v[182:185], v[54:57]
	v_mfma_f32_16x16x32_bf16 v[54:57], v[150:153], v[186:189], v[54:57]
	v_mfma_f32_16x16x32_bf16 v[50:53], v[174:177], v[182:185], v[50:53]
	v_mfma_f32_16x16x32_bf16 v[50:53], v[178:181], v[186:189], v[50:53]
	v_mfma_f32_16x16x32_bf16 v[38:41], v[146:149], v[190:193], v[38:41]
	v_mfma_f32_16x16x32_bf16 v[38:41], v[150:153], v[194:197], v[38:41]
	v_mfma_f32_16x16x32_bf16 v[34:37], v[174:177], v[190:193], v[34:37]
	v_mfma_f32_16x16x32_bf16 v[34:37], v[178:181], v[194:197], v[34:37]
	v_mfma_f32_16x16x32_bf16 v[22:25], v[146:149], v[202:205], v[22:25]
	v_mfma_f32_16x16x32_bf16 v[22:25], v[150:153], v[206:209], v[22:25]
	v_mfma_f32_16x16x32_bf16 v[18:21], v[174:177], v[202:205], v[18:21]
	v_mfma_f32_16x16x32_bf16 v[18:21], v[178:181], v[206:209], v[18:21]
	v_mfma_f32_16x16x32_bf16 v[6:9], v[146:149], v[210:213], v[6:9]
	v_mfma_f32_16x16x32_bf16 v[6:9], v[150:153], v[214:217], v[6:9]
	v_mfma_f32_16x16x32_bf16 v[2:5], v[174:177], v[210:213], v[2:5]
	v_mfma_f32_16x16x32_bf16 v[2:5], v[178:181], v[214:217], v[2:5]
	s_barrier
	s_add_i32 s78, 0, 0x18000
	s_add_i32 s79, 0, 0x1c000
	v_add_u32_e32 v142, s78, v199
	v_add_u32_e32 v162, s79, v199
	ds_read_b128 v[130:133], v142
	ds_read_b128 v[134:137], v142 offset:1024
	ds_read_b128 v[138:141], v142 offset:2048
	ds_read_b128 v[142:145], v142 offset:3072
	ds_read_b128 v[146:149], v162
	ds_read_b128 v[150:153], v162 offset:1024
	ds_read_b128 v[174:177], v162 offset:2048
	ds_read_b128 v[178:181], v162 offset:3072
	s_add_u32 s50, s56, 0x1000
	s_addc_u32 s51, s57, 0
	s_mov_b32 m0, s61
	v_lshl_add_u64 v[222:223], s[50:51], 0, v[154:155]
	ds_read_b128 v[182:185], v200 offset:32768
	ds_read_b128 v[186:189], v200 offset:33792
	ds_read_b128 v[190:193], v200 offset:34816
	ds_read_b128 v[194:197], v200 offset:35840
	ds_read_b128 v[202:205], v200 offset:36864
	ds_read_b128 v[206:209], v200 offset:37888
	ds_read_b128 v[210:213], v200 offset:38912
	ds_read_b128 v[214:217], v200 offset:39936
	global_load_lds_dwordx4 v[222:223], off
	v_lshl_add_u64 v[222:223], s[50:51], 0, v[158:159]
	s_mov_b32 m0, s62
	s_nop 0
	global_load_lds_dwordx4 v[222:223], off
	s_waitcnt vmcnt(8)
	s_waitcnt lgkmcnt(0)
	s_barrier
	v_mfma_f32_16x16x32_bf16 v[118:121], v[130:133], v[182:185], v[118:121]
	v_mfma_f32_16x16x32_bf16 v[118:121], v[134:137], v[186:189], v[118:121]
	v_mfma_f32_16x16x32_bf16 v[122:125], v[138:141], v[182:185], v[122:125]
	v_mfma_f32_16x16x32_bf16 v[122:125], v[142:145], v[186:189], v[122:125]
	v_mfma_f32_16x16x32_bf16 v[110:113], v[130:133], v[190:193], v[110:113]
	v_mfma_f32_16x16x32_bf16 v[110:113], v[134:137], v[194:197], v[110:113]
	v_mfma_f32_16x16x32_bf16 v[106:109], v[138:141], v[190:193], v[106:109]
	v_mfma_f32_16x16x32_bf16 v[106:109], v[142:145], v[194:197], v[106:109]
	v_mfma_f32_16x16x32_bf16 v[94:97], v[130:133], v[202:205], v[94:97]
	v_mfma_f32_16x16x32_bf16 v[94:97], v[134:137], v[206:209], v[94:97]
	v_mfma_f32_16x16x32_bf16 v[90:93], v[138:141], v[202:205], v[90:93]
	v_mfma_f32_16x16x32_bf16 v[90:93], v[142:145], v[206:209], v[90:93]
	v_mfma_f32_16x16x32_bf16 v[78:81], v[130:133], v[210:213], v[78:81]
	v_mfma_f32_16x16x32_bf16 v[78:81], v[134:137], v[214:217], v[78:81]
	v_mfma_f32_16x16x32_bf16 v[74:77], v[138:141], v[210:213], v[74:77]
	v_mfma_f32_16x16x32_bf16 v[74:77], v[142:145], v[214:217], v[74:77]
	v_mfma_f32_16x16x32_bf16 v[126:129], v[146:149], v[182:185], v[126:129]
	v_mfma_f32_16x16x32_bf16 v[126:129], v[150:153], v[186:189], v[126:129]
	v_mfma_f32_16x16x32_bf16 v[114:117], v[174:177], v[182:185], v[114:117]
	v_mfma_f32_16x16x32_bf16 v[114:117], v[178:181], v[186:189], v[114:117]
	v_mfma_f32_16x16x32_bf16 v[102:105], v[146:149], v[190:193], v[102:105]
	v_mfma_f32_16x16x32_bf16 v[102:105], v[150:153], v[194:197], v[102:105]
	v_mfma_f32_16x16x32_bf16 v[98:101], v[174:177], v[190:193], v[98:101]
	v_mfma_f32_16x16x32_bf16 v[98:101], v[178:181], v[194:197], v[98:101]
	v_mfma_f32_16x16x32_bf16 v[86:89], v[146:149], v[202:205], v[86:89]
	v_mfma_f32_16x16x32_bf16 v[86:89], v[150:153], v[206:209], v[86:89]
	v_mfma_f32_16x16x32_bf16 v[82:85], v[174:177], v[202:205], v[82:85]
	v_mfma_f32_16x16x32_bf16 v[82:85], v[178:181], v[206:209], v[82:85]
	v_mfma_f32_16x16x32_bf16 v[70:73], v[146:149], v[210:213], v[70:73]
	v_mfma_f32_16x16x32_bf16 v[70:73], v[150:153], v[214:217], v[70:73]
	v_mfma_f32_16x16x32_bf16 v[66:69], v[174:177], v[210:213], v[66:69]
	v_mfma_f32_16x16x32_bf16 v[66:69], v[178:181], v[214:217], v[66:69]
	s_barrier
	s_add_i32 s50, s78, s41
	v_lshl_add_u64 v[218:219], v[218:219], 0, s[14:15]
	s_mov_b32 m0, s50
	ds_read_b128 v[182:185], v200 offset:49152
	ds_read_b128 v[186:189], v200 offset:50176
	ds_read_b128 v[190:193], v200 offset:51200
	ds_read_b128 v[194:197], v200 offset:52224
	ds_read_b128 v[202:205], v200 offset:53248
	ds_read_b128 v[206:209], v200 offset:54272
	ds_read_b128 v[210:213], v200 offset:55296
	ds_read_b128 v[214:217], v200 offset:56320
	global_load_lds_dwordx4 v[218:219], off
	s_add_i32 m0, s50, 0x2000
	s_add_u32 s50, s54, 0x20080
	v_lshl_add_u64 v[218:219], v[220:221], 0, s[14:15]
	s_addc_u32 s51, s55, 0
	s_add_i32 s54, s79, s41
	global_load_lds_dwordx4 v[218:219], off
	v_lshl_add_u64 v[218:219], s[50:51], 0, v[156:157]
	s_mov_b32 m0, s54
	s_nop 0
	global_load_lds_dwordx4 v[218:219], off
	v_lshl_add_u64 v[218:219], s[50:51], 0, v[160:161]
	s_add_i32 m0, s54, 0x2000
	s_nop 0
	global_load_lds_dwordx4 v[218:219], off
	v_lshl_add_u64 v[218:219], s[52:53], 0, v[154:155]
	s_mov_b32 m0, s69
	s_nop 0
	global_load_lds_dwordx4 v[218:219], off
	v_lshl_add_u64 v[218:219], s[52:53], 0, v[158:159]
	s_mov_b32 m0, s70
	s_nop 0
	global_load_lds_dwordx4 v[218:219], off
	s_waitcnt vmcnt(8)
	s_waitcnt lgkmcnt(0)
	s_barrier
	v_mfma_f32_16x16x32_bf16 v[62:65], v[130:133], v[182:185], v[62:65]
	v_mfma_f32_16x16x32_bf16 v[62:65], v[134:137], v[186:189], v[62:65]
	v_mfma_f32_16x16x32_bf16 v[58:61], v[138:141], v[182:185], v[58:61]
	v_mfma_f32_16x16x32_bf16 v[58:61], v[142:145], v[186:189], v[58:61]
	v_mfma_f32_16x16x32_bf16 v[46:49], v[130:133], v[190:193], v[46:49]
	v_mfma_f32_16x16x32_bf16 v[46:49], v[134:137], v[194:197], v[46:49]
	v_mfma_f32_16x16x32_bf16 v[42:45], v[138:141], v[190:193], v[42:45]
	v_mfma_f32_16x16x32_bf16 v[42:45], v[142:145], v[194:197], v[42:45]
	v_mfma_f32_16x16x32_bf16 v[30:33], v[130:133], v[202:205], v[30:33]
	v_mfma_f32_16x16x32_bf16 v[30:33], v[134:137], v[206:209], v[30:33]
	v_mfma_f32_16x16x32_bf16 v[26:29], v[138:141], v[202:205], v[26:29]
	v_mfma_f32_16x16x32_bf16 v[26:29], v[142:145], v[206:209], v[26:29]
	v_mfma_f32_16x16x32_bf16 v[14:17], v[130:133], v[210:213], v[14:17]
	v_mfma_f32_16x16x32_bf16 v[14:17], v[134:137], v[214:217], v[14:17]
	v_mfma_f32_16x16x32_bf16 v[10:13], v[138:141], v[210:213], v[10:13]
	v_mfma_f32_16x16x32_bf16 v[10:13], v[142:145], v[214:217], v[10:13]
	v_mfma_f32_16x16x32_bf16 v[54:57], v[146:149], v[182:185], v[54:57]
	v_mfma_f32_16x16x32_bf16 v[54:57], v[150:153], v[186:189], v[54:57]
	v_mfma_f32_16x16x32_bf16 v[50:53], v[174:177], v[182:185], v[50:53]
	v_mfma_f32_16x16x32_bf16 v[50:53], v[178:181], v[186:189], v[50:53]
	v_mfma_f32_16x16x32_bf16 v[38:41], v[146:149], v[190:193], v[38:41]
	v_mfma_f32_16x16x32_bf16 v[38:41], v[150:153], v[194:197], v[38:41]
	v_mfma_f32_16x16x32_bf16 v[34:37], v[174:177], v[190:193], v[34:37]
	v_mfma_f32_16x16x32_bf16 v[34:37], v[178:181], v[194:197], v[34:37]
	v_mfma_f32_16x16x32_bf16 v[22:25], v[146:149], v[202:205], v[22:25]
	v_mfma_f32_16x16x32_bf16 v[22:25], v[150:153], v[206:209], v[22:25]
	v_mfma_f32_16x16x32_bf16 v[18:21], v[174:177], v[202:205], v[18:21]
	v_mfma_f32_16x16x32_bf16 v[18:21], v[178:181], v[206:209], v[18:21]
	v_mfma_f32_16x16x32_bf16 v[6:9], v[146:149], v[210:213], v[6:9]
	v_mfma_f32_16x16x32_bf16 v[6:9], v[150:153], v[214:217], v[6:9]
	v_mfma_f32_16x16x32_bf16 v[2:5], v[174:177], v[210:213], v[2:5]
	v_mfma_f32_16x16x32_bf16 v[2:5], v[178:181], v[214:217], v[2:5]
	s_barrier
	s_add_u32 s23, s23, 0x100
	s_addc_u32 s25, s25, 0
	s_add_u32 s34, s34, 0x800000
	s_addc_u32 s35, s35, 0
	s_cmp_ge_i32 s31, s67
	s_mov_b32 s52, s31
	s_cbranch_scc0 .LBB0_599

.LBB0_740:
	v_add_u32_e32 v144, s88, v188
	v_add_u32_e32 v160, s89, v188
	ds_read_b128 v[132:135], v144
	ds_read_b128 v[136:139], v144 offset:1024
	ds_read_b128 v[140:143], v144 offset:2048
	ds_read_b128 v[144:147], v144 offset:3072
	ds_read_b128 v[148:151], v160
	ds_read_b128 v[152:155], v160 offset:1024
	ds_read_b128 v[156:159], v160 offset:2048
	ds_read_b128 v[184:187], v160 offset:3072
	s_add_i32 s92, s55, 2
	s_add_u32 s50, s60, 0x3fc000
	s_addc_u32 s51, s61, 0
	s_cmp_eq_u32 s87, s55
	s_cselect_b32 s70, s64, s50
	s_cselect_b32 s71, s65, s51
	s_cselect_b32 s69, s67, s53
	s_cselect_b32 s68, s66, s13
	s_add_u32 s62, s70, 0x400000
	s_addc_u32 s63, s71, 0
	v_lshl_add_u64 v[160:161], s[60:61], 0, v[176:177]
	s_add_i32 m0, s77, 0xc000
	ds_read_b128 v[192:195], v189
	ds_read_b128 v[196:199], v189 offset:1024
	ds_read_b128 v[200:203], v189 offset:2048
	ds_read_b128 v[204:207], v189 offset:3072
	ds_read_b128 v[208:211], v189 offset:4096
	ds_read_b128 v[212:215], v189 offset:5120
	ds_read_b128 v[216:219], v189 offset:6144
	ds_read_b128 v[220:223], v189 offset:7168
	global_load_lds_dwordx4 v[160:161], off
	v_lshl_add_u64 v[160:161], s[60:61], 0, v[178:179]
	s_add_i32 m0, s77, 0xe000
	s_nop 0
	global_load_lds_dwordx4 v[160:161], off
	s_waitcnt vmcnt(8)
	s_waitcnt lgkmcnt(0)
	s_barrier
	v_mfma_f32_16x16x32_bf16 v[30:33], v[132:135], v[192:195], v[30:33]
	v_mfma_f32_16x16x32_bf16 v[30:33], v[136:139], v[196:199], v[30:33]
	v_mfma_f32_16x16x32_bf16 v[26:29], v[140:143], v[192:195], v[26:29]
	v_mfma_f32_16x16x32_bf16 v[26:29], v[144:147], v[196:199], v[26:29]
	v_mfma_f32_16x16x32_bf16 v[86:89], v[132:135], v[200:203], v[86:89]
	v_mfma_f32_16x16x32_bf16 v[86:89], v[136:139], v[204:207], v[86:89]
	v_mfma_f32_16x16x32_bf16 v[66:69], v[140:143], v[200:203], v[66:69]
	v_mfma_f32_16x16x32_bf16 v[66:69], v[144:147], v[204:207], v[66:69]
	v_mfma_f32_16x16x32_bf16 v[94:97], v[132:135], v[208:211], v[94:97]
	v_mfma_f32_16x16x32_bf16 v[94:97], v[136:139], v[212:215], v[94:97]
	v_mfma_f32_16x16x32_bf16 v[82:85], v[140:143], v[208:211], v[82:85]
	v_mfma_f32_16x16x32_bf16 v[82:85], v[144:147], v[212:215], v[82:85]
	v_mfma_f32_16x16x32_bf16 v[90:93], v[132:135], v[216:219], v[90:93]
	v_mfma_f32_16x16x32_bf16 v[90:93], v[136:139], v[220:223], v[90:93]
	v_mfma_f32_16x16x32_bf16 v[78:81], v[140:143], v[216:219], v[78:81]
	v_mfma_f32_16x16x32_bf16 v[78:81], v[144:147], v[220:223], v[78:81]
	v_mfma_f32_16x16x32_bf16 v[50:53], v[148:151], v[192:195], v[50:53]
	v_mfma_f32_16x16x32_bf16 v[50:53], v[152:155], v[196:199], v[50:53]
	v_mfma_f32_16x16x32_bf16 v[42:45], v[156:159], v[192:195], v[42:45]
	v_mfma_f32_16x16x32_bf16 v[42:45], v[184:187], v[196:199], v[42:45]
	v_mfma_f32_16x16x32_bf16 v[14:17], v[148:151], v[200:203], v[14:17]
	v_mfma_f32_16x16x32_bf16 v[14:17], v[152:155], v[204:207], v[14:17]
	v_mfma_f32_16x16x32_bf16 v[2:5], v[156:159], v[200:203], v[2:5]
	v_mfma_f32_16x16x32_bf16 v[2:5], v[184:187], v[204:207], v[2:5]
	v_mfma_f32_16x16x32_bf16 v[22:25], v[148:151], v[208:211], v[22:25]
	v_mfma_f32_16x16x32_bf16 v[22:25], v[152:155], v[212:215], v[22:25]
	v_mfma_f32_16x16x32_bf16 v[10:13], v[156:159], v[208:211], v[10:13]
	v_mfma_f32_16x16x32_bf16 v[10:13], v[184:187], v[212:215], v[10:13]
	v_mfma_f32_16x16x32_bf16 v[18:21], v[148:151], v[216:219], v[18:21]
	v_mfma_f32_16x16x32_bf16 v[18:21], v[152:155], v[220:223], v[18:21]
	v_mfma_f32_16x16x32_bf16 v[6:9], v[156:159], v[216:219], v[6:9]
	v_mfma_f32_16x16x32_bf16 v[6:9], v[184:187], v[220:223], v[6:9]
	s_barrier
	s_add_i32 s50, s88, s76
	v_lshl_add_u64 v[160:161], s[68:69], 0, v[164:165]
	s_mov_b32 m0, s50
	ds_read_b128 v[192:195], v189 offset:16384
	ds_read_b128 v[196:199], v189 offset:17408
	ds_read_b128 v[200:203], v189 offset:18432
	ds_read_b128 v[204:207], v189 offset:19456
	ds_read_b128 v[208:211], v189 offset:20480
	ds_read_b128 v[212:215], v189 offset:21504
	ds_read_b128 v[216:219], v189 offset:22528
	ds_read_b128 v[220:223], v189 offset:23552
	global_load_lds_dwordx4 v[160:161], off
	s_add_i32 m0, s50, 0x2000
	s_add_u32 s50, s68, 0x10000
	v_lshl_add_u64 v[224:225], s[68:69], 0, v[168:169]
	s_addc_u32 s51, s69, 0
	s_add_i32 s55, s89, s76
	global_load_lds_dwordx4 v[224:225], off
	v_lshl_add_u64 v[226:227], s[50:51], 0, v[164:165]
	s_mov_b32 m0, s55
	s_nop 0
	global_load_lds_dwordx4 v[226:227], off
	v_lshl_add_u64 v[226:227], s[50:51], 0, v[168:169]
	s_add_i32 m0, s55, 0x2000
	s_nop 0
	global_load_lds_dwordx4 v[226:227], off
	v_lshl_add_u64 v[226:227], s[70:71], 0, v[162:163]
	s_mov_b32 m0, s77
	s_nop 0
	global_load_lds_dwordx4 v[226:227], off
	v_lshl_add_u64 v[226:227], s[70:71], 0, v[166:167]
	s_mov_b32 m0, s78
	s_nop 0
	global_load_lds_dwordx4 v[226:227], off
	s_waitcnt vmcnt(8)
	s_waitcnt lgkmcnt(0)
	s_barrier
	v_mfma_f32_16x16x32_bf16 v[118:121], v[132:135], v[192:195], v[118:121]
	v_mfma_f32_16x16x32_bf16 v[118:121], v[136:139], v[196:199], v[118:121]
	v_mfma_f32_16x16x32_bf16 v[102:105], v[140:143], v[192:195], v[102:105]
	v_mfma_f32_16x16x32_bf16 v[102:105], v[144:147], v[196:199], v[102:105]
	v_mfma_f32_16x16x32_bf16 v[114:117], v[132:135], v[200:203], v[114:117]
	v_mfma_f32_16x16x32_bf16 v[114:117], v[136:139], v[204:207], v[114:117]
	v_mfma_f32_16x16x32_bf16 v[98:101], v[140:143], v[200:203], v[98:101]
	v_mfma_f32_16x16x32_bf16 v[98:101], v[144:147], v[204:207], v[98:101]
	v_mfma_f32_16x16x32_bf16 v[126:129], v[132:135], v[208:211], v[126:129]
	v_mfma_f32_16x16x32_bf16 v[126:129], v[136:139], v[212:215], v[126:129]
	v_mfma_f32_16x16x32_bf16 v[110:113], v[140:143], v[208:211], v[110:113]
	v_mfma_f32_16x16x32_bf16 v[110:113], v[144:147], v[212:215], v[110:113]
	v_mfma_f32_16x16x32_bf16 v[122:125], v[132:135], v[216:219], v[122:125]
	v_mfma_f32_16x16x32_bf16 v[122:125], v[136:139], v[220:223], v[122:125]
	v_mfma_f32_16x16x32_bf16 v[106:109], v[140:143], v[216:219], v[106:109]
	v_mfma_f32_16x16x32_bf16 v[106:109], v[144:147], v[220:223], v[106:109]
	v_mfma_f32_16x16x32_bf16 v[62:65], v[148:151], v[192:195], v[62:65]
	v_mfma_f32_16x16x32_bf16 v[62:65], v[152:155], v[196:199], v[62:65]
	v_mfma_f32_16x16x32_bf16 v[38:41], v[156:159], v[192:195], v[38:41]
	v_mfma_f32_16x16x32_bf16 v[38:41], v[184:187], v[196:199], v[38:41]
	v_mfma_f32_16x16x32_bf16 v[58:61], v[148:151], v[200:203], v[58:61]
	v_mfma_f32_16x16x32_bf16 v[58:61], v[152:155], v[204:207], v[58:61]
	v_mfma_f32_16x16x32_bf16 v[34:37], v[156:159], v[200:203], v[34:37]
	v_mfma_f32_16x16x32_bf16 v[34:37], v[184:187], v[204:207], v[34:37]
	v_mfma_f32_16x16x32_bf16 v[74:77], v[148:151], v[208:211], v[74:77]
	v_mfma_f32_16x16x32_bf16 v[74:77], v[152:155], v[212:215], v[74:77]
	v_mfma_f32_16x16x32_bf16 v[54:57], v[156:159], v[208:211], v[54:57]
	v_mfma_f32_16x16x32_bf16 v[54:57], v[184:187], v[212:215], v[54:57]
	v_mfma_f32_16x16x32_bf16 v[70:73], v[148:151], v[216:219], v[70:73]
	v_mfma_f32_16x16x32_bf16 v[70:73], v[152:155], v[220:223], v[70:73]
	v_mfma_f32_16x16x32_bf16 v[46:49], v[156:159], v[216:219], v[46:49]
	v_mfma_f32_16x16x32_bf16 v[46:49], v[184:187], v[220:223], v[46:49]
	s_barrier
	s_add_i32 s55, 0, 0x18000
	s_add_i32 s93, 0, 0x1c000
	v_add_u32_e32 v144, s55, v188
	v_add_u32_e32 v184, s93, v188
	ds_read_b128 v[132:135], v144
	ds_read_b128 v[136:139], v144 offset:1024
	ds_read_b128 v[140:143], v144 offset:2048
	ds_read_b128 v[144:147], v144 offset:3072
	ds_read_b128 v[148:151], v184
	ds_read_b128 v[152:155], v184 offset:1024
	ds_read_b128 v[156:159], v184 offset:2048
	ds_read_b128 v[184:187], v184 offset:3072
	s_add_u32 s50, s70, 0x4000
	s_addc_u32 s51, s71, 0
	s_mov_b32 m0, s79
	v_lshl_add_u64 v[226:227], s[50:51], 0, v[162:163]
	ds_read_b128 v[192:195], v189 offset:32768
	ds_read_b128 v[196:199], v189 offset:33792
	ds_read_b128 v[200:203], v189 offset:34816
	ds_read_b128 v[204:207], v189 offset:35840
	ds_read_b128 v[208:211], v189 offset:36864
	ds_read_b128 v[212:215], v189 offset:37888
	ds_read_b128 v[216:219], v189 offset:38912
	ds_read_b128 v[220:223], v189 offset:39936
	global_load_lds_dwordx4 v[226:227], off
	v_lshl_add_u64 v[226:227], s[50:51], 0, v[166:167]
	s_mov_b32 m0, s80
	s_nop 0
	global_load_lds_dwordx4 v[226:227], off
	s_waitcnt vmcnt(8)
	s_waitcnt lgkmcnt(0)
	s_barrier
	v_mfma_f32_16x16x32_bf16 v[30:33], v[132:135], v[192:195], v[30:33]
	v_mfma_f32_16x16x32_bf16 v[30:33], v[136:139], v[196:199], v[30:33]
	v_mfma_f32_16x16x32_bf16 v[26:29], v[140:143], v[192:195], v[26:29]
	v_mfma_f32_16x16x32_bf16 v[26:29], v[144:147], v[196:199], v[26:29]
	v_mfma_f32_16x16x32_bf16 v[86:89], v[132:135], v[200:203], v[86:89]
	v_mfma_f32_16x16x32_bf16 v[86:89], v[136:139], v[204:207], v[86:89]
	v_mfma_f32_16x16x32_bf16 v[66:69], v[140:143], v[200:203], v[66:69]
	v_mfma_f32_16x16x32_bf16 v[66:69], v[144:147], v[204:207], v[66:69]
	v_mfma_f32_16x16x32_bf16 v[94:97], v[132:135], v[208:211], v[94:97]
	v_mfma_f32_16x16x32_bf16 v[94:97], v[136:139], v[212:215], v[94:97]
	v_mfma_f32_16x16x32_bf16 v[82:85], v[140:143], v[208:211], v[82:85]
	v_mfma_f32_16x16x32_bf16 v[82:85], v[144:147], v[212:215], v[82:85]
	v_mfma_f32_16x16x32_bf16 v[90:93], v[132:135], v[216:219], v[90:93]
	v_mfma_f32_16x16x32_bf16 v[90:93], v[136:139], v[220:223], v[90:93]
	v_mfma_f32_16x16x32_bf16 v[78:81], v[140:143], v[216:219], v[78:81]
	v_mfma_f32_16x16x32_bf16 v[78:81], v[144:147], v[220:223], v[78:81]
	v_mfma_f32_16x16x32_bf16 v[50:53], v[148:151], v[192:195], v[50:53]
	v_mfma_f32_16x16x32_bf16 v[50:53], v[152:155], v[196:199], v[50:53]
	v_mfma_f32_16x16x32_bf16 v[42:45], v[156:159], v[192:195], v[42:45]
	v_mfma_f32_16x16x32_bf16 v[42:45], v[184:187], v[196:199], v[42:45]
	v_mfma_f32_16x16x32_bf16 v[14:17], v[148:151], v[200:203], v[14:17]
	v_mfma_f32_16x16x32_bf16 v[14:17], v[152:155], v[204:207], v[14:17]
	v_mfma_f32_16x16x32_bf16 v[2:5], v[156:159], v[200:203], v[2:5]
	v_mfma_f32_16x16x32_bf16 v[2:5], v[184:187], v[204:207], v[2:5]
	v_mfma_f32_16x16x32_bf16 v[22:25], v[148:151], v[208:211], v[22:25]
	v_mfma_f32_16x16x32_bf16 v[22:25], v[152:155], v[212:215], v[22:25]
	v_mfma_f32_16x16x32_bf16 v[10:13], v[156:159], v[208:211], v[10:13]
	v_mfma_f32_16x16x32_bf16 v[10:13], v[184:187], v[212:215], v[10:13]
	v_mfma_f32_16x16x32_bf16 v[18:21], v[148:151], v[216:219], v[18:21]
	v_mfma_f32_16x16x32_bf16 v[18:21], v[152:155], v[220:223], v[18:21]
	v_mfma_f32_16x16x32_bf16 v[6:9], v[156:159], v[216:219], v[6:9]
	v_mfma_f32_16x16x32_bf16 v[6:9], v[184:187], v[220:223], v[6:9]
	s_barrier
	s_add_i32 s50, s55, s76
	v_lshl_add_u64 v[160:161], v[160:161], 0, s[14:15]
	s_mov_b32 m0, s50
	ds_read_b128 v[192:195], v189 offset:49152
	ds_read_b128 v[196:199], v189 offset:50176
	ds_read_b128 v[200:203], v189 offset:51200
	ds_read_b128 v[204:207], v189 offset:52224
	ds_read_b128 v[208:211], v189 offset:53248
	ds_read_b128 v[212:215], v189 offset:54272
	ds_read_b128 v[216:219], v189 offset:55296
	ds_read_b128 v[220:223], v189 offset:56320
	global_load_lds_dwordx4 v[160:161], off
	s_add_i32 m0, s50, 0x2000
	s_add_u32 s50, s68, 0x10080
	v_lshl_add_u64 v[160:161], v[224:225], 0, s[14:15]
	s_addc_u32 s51, s69, 0
	s_add_i32 s55, s93, s76
	global_load_lds_dwordx4 v[160:161], off
	v_lshl_add_u64 v[160:161], s[50:51], 0, v[164:165]
	s_mov_b32 m0, s55
	s_nop 0
	global_load_lds_dwordx4 v[160:161], off
	v_lshl_add_u64 v[160:161], s[50:51], 0, v[168:169]
	s_add_i32 m0, s55, 0x2000
	s_nop 0
	global_load_lds_dwordx4 v[160:161], off
	v_lshl_add_u64 v[160:161], s[62:63], 0, v[162:163]
	s_mov_b32 m0, s84
	s_nop 0
	global_load_lds_dwordx4 v[160:161], off
	v_lshl_add_u64 v[160:161], s[62:63], 0, v[166:167]
	s_mov_b32 m0, s85
	s_nop 0
	global_load_lds_dwordx4 v[160:161], off
	s_waitcnt vmcnt(8)
	s_waitcnt lgkmcnt(0)
	s_barrier
	v_mfma_f32_16x16x32_bf16 v[118:121], v[132:135], v[192:195], v[118:121]
	v_mfma_f32_16x16x32_bf16 v[118:121], v[136:139], v[196:199], v[118:121]
	v_mfma_f32_16x16x32_bf16 v[102:105], v[140:143], v[192:195], v[102:105]
	v_mfma_f32_16x16x32_bf16 v[102:105], v[144:147], v[196:199], v[102:105]
	v_mfma_f32_16x16x32_bf16 v[114:117], v[132:135], v[200:203], v[114:117]
	v_mfma_f32_16x16x32_bf16 v[114:117], v[136:139], v[204:207], v[114:117]
	v_mfma_f32_16x16x32_bf16 v[98:101], v[140:143], v[200:203], v[98:101]
	v_mfma_f32_16x16x32_bf16 v[98:101], v[144:147], v[204:207], v[98:101]
	v_mfma_f32_16x16x32_bf16 v[126:129], v[132:135], v[208:211], v[126:129]
	v_mfma_f32_16x16x32_bf16 v[126:129], v[136:139], v[212:215], v[126:129]
	v_mfma_f32_16x16x32_bf16 v[110:113], v[140:143], v[208:211], v[110:113]
	v_mfma_f32_16x16x32_bf16 v[110:113], v[144:147], v[212:215], v[110:113]
	v_mfma_f32_16x16x32_bf16 v[122:125], v[132:135], v[216:219], v[122:125]
	v_mfma_f32_16x16x32_bf16 v[122:125], v[136:139], v[220:223], v[122:125]
	v_mfma_f32_16x16x32_bf16 v[106:109], v[140:143], v[216:219], v[106:109]
	v_mfma_f32_16x16x32_bf16 v[106:109], v[144:147], v[220:223], v[106:109]
	v_mfma_f32_16x16x32_bf16 v[62:65], v[148:151], v[192:195], v[62:65]
	v_mfma_f32_16x16x32_bf16 v[62:65], v[152:155], v[196:199], v[62:65]
	v_mfma_f32_16x16x32_bf16 v[38:41], v[156:159], v[192:195], v[38:41]
	v_mfma_f32_16x16x32_bf16 v[38:41], v[184:187], v[196:199], v[38:41]
	v_mfma_f32_16x16x32_bf16 v[58:61], v[148:151], v[200:203], v[58:61]
	v_mfma_f32_16x16x32_bf16 v[58:61], v[152:155], v[204:207], v[58:61]
	v_mfma_f32_16x16x32_bf16 v[34:37], v[156:159], v[200:203], v[34:37]
	v_mfma_f32_16x16x32_bf16 v[34:37], v[184:187], v[204:207], v[34:37]
	v_mfma_f32_16x16x32_bf16 v[74:77], v[148:151], v[208:211], v[74:77]
	v_mfma_f32_16x16x32_bf16 v[74:77], v[152:155], v[212:215], v[74:77]
	v_mfma_f32_16x16x32_bf16 v[54:57], v[156:159], v[208:211], v[54:57]
	v_mfma_f32_16x16x32_bf16 v[54:57], v[184:187], v[212:215], v[54:57]
	v_mfma_f32_16x16x32_bf16 v[70:73], v[148:151], v[216:219], v[70:73]
	v_mfma_f32_16x16x32_bf16 v[70:73], v[152:155], v[220:223], v[70:73]
	v_mfma_f32_16x16x32_bf16 v[46:49], v[156:159], v[216:219], v[46:49]
	v_mfma_f32_16x16x32_bf16 v[46:49], v[184:187], v[220:223], v[46:49]
	s_barrier
	s_add_u32 s13, s13, 0x100
	s_addc_u32 s53, s53, 0
	s_add_u32 s60, s60, 0x800000
	s_addc_u32 s61, s61, 0
	s_cmp_ge_i32 s92, s83
	s_cbranch_scc0 .LBB0_738

.LBB0_872:
	v_add_u32_e32 v162, s73, v140
	v_add_u32_e32 v178, s74, v140
	ds_read_b128 v[150:153], v162
	ds_read_b128 v[154:157], v162 offset:1024
	ds_read_b128 v[158:161], v162 offset:2048
	ds_read_b128 v[162:165], v162 offset:3072
	ds_read_b128 v[166:169], v178
	ds_read_b128 v[170:173], v178 offset:1024
	ds_read_b128 v[174:177], v178 offset:2048
	ds_read_b128 v[178:181], v178 offset:3072
	s_add_i32 s77, s52, 2
	s_add_u32 s50, s34, 0xfffc0080
	s_addc_u32 s51, s35, -1
	s_cmp_eq_u32 s70, s52
	s_cselect_b32 s52, s30, s21
	s_cselect_b32 s55, s29, s51
	s_cselect_b32 s54, s28, s50
	s_cselect_b32 s53, s31, s23
	v_lshl_add_u64 v[214:215], s[34:35], 0, v[132:133]
	s_add_i32 m0, s60, 0xc000
	ds_read_b128 v[182:185], v149
	ds_read_b128 v[186:189], v149 offset:1024
	ds_read_b128 v[190:193], v149 offset:2048
	ds_read_b128 v[194:197], v149 offset:3072
	ds_read_b128 v[198:201], v149 offset:4096
	ds_read_b128 v[202:205], v149 offset:5120
	ds_read_b128 v[206:209], v149 offset:6144
	ds_read_b128 v[210:213], v149 offset:7168
	global_load_lds_dwordx4 v[214:215], off
	v_lshl_add_u64 v[214:215], s[34:35], 0, v[134:135]
	s_add_i32 m0, s60, 0xe000
	s_nop 0
	global_load_lds_dwordx4 v[214:215], off
	s_waitcnt vmcnt(8)
	s_waitcnt lgkmcnt(0)
	s_barrier
	v_mfma_f32_16x16x32_bf16 v[78:81], v[150:153], v[182:185], v[78:81]
	v_mfma_f32_16x16x32_bf16 v[78:81], v[154:157], v[186:189], v[78:81]
	v_mfma_f32_16x16x32_bf16 v[14:17], v[158:161], v[182:185], v[14:17]
	v_mfma_f32_16x16x32_bf16 v[14:17], v[162:165], v[186:189], v[14:17]
	v_mfma_f32_16x16x32_bf16 v[66:69], v[150:153], v[190:193], v[66:69]
	v_mfma_f32_16x16x32_bf16 v[66:69], v[154:157], v[194:197], v[66:69]
	v_mfma_f32_16x16x32_bf16 v[2:5], v[158:161], v[190:193], v[2:5]
	v_mfma_f32_16x16x32_bf16 v[2:5], v[162:165], v[194:197], v[2:5]
	v_mfma_f32_16x16x32_bf16 v[70:73], v[150:153], v[198:201], v[70:73]
	v_mfma_f32_16x16x32_bf16 v[70:73], v[154:157], v[202:205], v[70:73]
	v_mfma_f32_16x16x32_bf16 v[6:9], v[158:161], v[198:201], v[6:9]
	v_mfma_f32_16x16x32_bf16 v[6:9], v[162:165], v[202:205], v[6:9]
	v_mfma_f32_16x16x32_bf16 v[74:77], v[150:153], v[206:209], v[74:77]
	v_mfma_f32_16x16x32_bf16 v[74:77], v[154:157], v[210:213], v[74:77]
	v_mfma_f32_16x16x32_bf16 v[10:13], v[158:161], v[206:209], v[10:13]
	v_mfma_f32_16x16x32_bf16 v[10:13], v[162:165], v[210:213], v[10:13]
	v_mfma_f32_16x16x32_bf16 v[98:101], v[166:169], v[182:185], v[98:101]
	v_mfma_f32_16x16x32_bf16 v[98:101], v[170:173], v[186:189], v[98:101]
	v_mfma_f32_16x16x32_bf16 v[34:37], v[174:177], v[182:185], v[34:37]
	v_mfma_f32_16x16x32_bf16 v[34:37], v[178:181], v[186:189], v[34:37]
	v_mfma_f32_16x16x32_bf16 v[82:85], v[166:169], v[190:193], v[82:85]
	v_mfma_f32_16x16x32_bf16 v[82:85], v[170:173], v[194:197], v[82:85]
	v_mfma_f32_16x16x32_bf16 v[18:21], v[174:177], v[190:193], v[18:21]
	v_mfma_f32_16x16x32_bf16 v[18:21], v[178:181], v[194:197], v[18:21]
	v_mfma_f32_16x16x32_bf16 v[86:89], v[166:169], v[198:201], v[86:89]
	v_mfma_f32_16x16x32_bf16 v[86:89], v[170:173], v[202:205], v[86:89]
	v_mfma_f32_16x16x32_bf16 v[22:25], v[174:177], v[198:201], v[22:25]
	v_mfma_f32_16x16x32_bf16 v[22:25], v[178:181], v[202:205], v[22:25]
	v_mfma_f32_16x16x32_bf16 v[94:97], v[166:169], v[206:209], v[94:97]
	v_mfma_f32_16x16x32_bf16 v[94:97], v[170:173], v[210:213], v[94:97]
	v_mfma_f32_16x16x32_bf16 v[30:33], v[174:177], v[206:209], v[30:33]
	v_mfma_f32_16x16x32_bf16 v[30:33], v[178:181], v[210:213], v[30:33]
	s_barrier
	s_add_i32 s50, s73, s15
	v_lshl_add_u64 v[214:215], s[52:53], 0, v[228:229]
	s_mov_b32 m0, s50
	ds_read_b128 v[182:185], v149 offset:16384
	ds_read_b128 v[186:189], v149 offset:17408
	ds_read_b128 v[190:193], v149 offset:18432
	ds_read_b128 v[194:197], v149 offset:19456
	ds_read_b128 v[198:201], v149 offset:20480
	ds_read_b128 v[202:205], v149 offset:21504
	ds_read_b128 v[206:209], v149 offset:22528
	ds_read_b128 v[210:213], v149 offset:23552
	global_load_lds_dwordx4 v[214:215], off
	s_add_i32 m0, s50, 0x2000
	s_add_u32 s50, s52, 0x40000
	v_lshl_add_u64 v[216:217], s[52:53], 0, v[232:233]
	s_addc_u32 s51, s53, 0
	s_add_i32 s78, s74, s15
	global_load_lds_dwordx4 v[216:217], off
	v_lshl_add_u64 v[218:219], s[50:51], 0, v[228:229]
	s_mov_b32 m0, s78
	v_lshl_add_u64 v[220:221], s[54:55], 0, v[230:231]
	global_load_lds_dwordx4 v[218:219], off
	v_lshl_add_u64 v[218:219], s[50:51], 0, v[232:233]
	s_add_i32 m0, s78, 0x2000
	s_nop 0
	global_load_lds_dwordx4 v[218:219], off
	v_lshl_add_u64 v[218:219], s[54:55], 0, v[226:227]
	s_mov_b32 m0, s60
	s_nop 0
	global_load_lds_dwordx4 v[218:219], off
	s_mov_b32 m0, s61
	s_nop 0
	global_load_lds_dwordx4 v[220:221], off
	s_waitcnt vmcnt(8)
	s_waitcnt lgkmcnt(0)
	s_barrier
	v_mfma_f32_16x16x32_bf16 v[90:93], v[150:153], v[182:185], v[90:93]
	v_mfma_f32_16x16x32_bf16 v[90:93], v[154:157], v[186:189], v[90:93]
	v_mfma_f32_16x16x32_bf16 v[26:29], v[158:161], v[182:185], v[26:29]
	v_mfma_f32_16x16x32_bf16 v[26:29], v[162:165], v[186:189], v[26:29]
	v_mfma_f32_16x16x32_bf16 v[102:105], v[150:153], v[190:193], v[102:105]
	v_mfma_f32_16x16x32_bf16 v[102:105], v[154:157], v[194:197], v[102:105]
	v_mfma_f32_16x16x32_bf16 v[38:41], v[158:161], v[190:193], v[38:41]
	v_mfma_f32_16x16x32_bf16 v[38:41], v[162:165], v[194:197], v[38:41]
	v_mfma_f32_16x16x32_bf16 v[106:109], v[150:153], v[198:201], v[106:109]
	v_mfma_f32_16x16x32_bf16 v[106:109], v[154:157], v[202:205], v[106:109]
	v_mfma_f32_16x16x32_bf16 v[42:45], v[158:161], v[198:201], v[42:45]
	v_mfma_f32_16x16x32_bf16 v[42:45], v[162:165], v[202:205], v[42:45]
	v_mfma_f32_16x16x32_bf16 v[110:113], v[150:153], v[206:209], v[110:113]
	v_mfma_f32_16x16x32_bf16 v[110:113], v[154:157], v[210:213], v[110:113]
	v_mfma_f32_16x16x32_bf16 v[46:49], v[158:161], v[206:209], v[46:49]
	v_mfma_f32_16x16x32_bf16 v[46:49], v[162:165], v[210:213], v[46:49]
	v_mfma_f32_16x16x32_bf16 v[114:117], v[166:169], v[182:185], v[114:117]
	v_mfma_f32_16x16x32_bf16 v[114:117], v[170:173], v[186:189], v[114:117]
	v_mfma_f32_16x16x32_bf16 v[50:53], v[174:177], v[182:185], v[50:53]
	v_mfma_f32_16x16x32_bf16 v[50:53], v[178:181], v[186:189], v[50:53]
	v_mfma_f32_16x16x32_bf16 v[118:121], v[166:169], v[190:193], v[118:121]
	v_mfma_f32_16x16x32_bf16 v[118:121], v[170:173], v[194:197], v[118:121]
	v_mfma_f32_16x16x32_bf16 v[54:57], v[174:177], v[190:193], v[54:57]
	v_mfma_f32_16x16x32_bf16 v[54:57], v[178:181], v[194:197], v[54:57]
	v_mfma_f32_16x16x32_bf16 v[122:125], v[166:169], v[198:201], v[122:125]
	v_mfma_f32_16x16x32_bf16 v[122:125], v[170:173], v[202:205], v[122:125]
	v_mfma_f32_16x16x32_bf16 v[58:61], v[174:177], v[198:201], v[58:61]
	v_mfma_f32_16x16x32_bf16 v[58:61], v[178:181], v[202:205], v[58:61]
	v_mfma_f32_16x16x32_bf16 v[126:129], v[166:169], v[206:209], v[126:129]
	v_mfma_f32_16x16x32_bf16 v[126:129], v[170:173], v[210:213], v[126:129]
	v_mfma_f32_16x16x32_bf16 v[62:65], v[174:177], v[206:209], v[62:65]
	v_mfma_f32_16x16x32_bf16 v[62:65], v[178:181], v[210:213], v[62:65]
	s_barrier
	s_add_i32 s78, 0, 0x18000
	s_add_i32 s79, 0, 0x1c000
	v_add_u32_e32 v162, s78, v140
	v_add_u32_e32 v178, s79, v140
	ds_read_b128 v[150:153], v162
	ds_read_b128 v[154:157], v162 offset:1024
	ds_read_b128 v[158:161], v162 offset:2048
	ds_read_b128 v[162:165], v162 offset:3072
	ds_read_b128 v[166:169], v178
	ds_read_b128 v[170:173], v178 offset:1024
	ds_read_b128 v[174:177], v178 offset:2048
	ds_read_b128 v[178:181], v178 offset:3072
	s_add_u32 s50, s54, 0x40000
	s_addc_u32 s51, s55, 0
	s_mov_b32 m0, s62
	v_lshl_add_u64 v[222:223], s[50:51], 0, v[226:227]
	ds_read_b128 v[182:185], v149 offset:32768
	ds_read_b128 v[186:189], v149 offset:33792
	ds_read_b128 v[190:193], v149 offset:34816
	ds_read_b128 v[194:197], v149 offset:35840
	ds_read_b128 v[198:201], v149 offset:36864
	ds_read_b128 v[202:205], v149 offset:37888
	ds_read_b128 v[206:209], v149 offset:38912
	ds_read_b128 v[210:213], v149 offset:39936
	global_load_lds_dwordx4 v[222:223], off
	v_lshl_add_u64 v[222:223], s[50:51], 0, v[230:231]
	s_mov_b32 m0, s63
	s_nop 0
	global_load_lds_dwordx4 v[222:223], off
	s_waitcnt vmcnt(8)
	s_waitcnt lgkmcnt(0)
	s_barrier
	v_mfma_f32_16x16x32_bf16 v[78:81], v[150:153], v[182:185], v[78:81]
	v_mfma_f32_16x16x32_bf16 v[78:81], v[154:157], v[186:189], v[78:81]
	v_mfma_f32_16x16x32_bf16 v[14:17], v[158:161], v[182:185], v[14:17]
	v_mfma_f32_16x16x32_bf16 v[14:17], v[162:165], v[186:189], v[14:17]
	v_mfma_f32_16x16x32_bf16 v[66:69], v[150:153], v[190:193], v[66:69]
	v_mfma_f32_16x16x32_bf16 v[66:69], v[154:157], v[194:197], v[66:69]
	v_mfma_f32_16x16x32_bf16 v[2:5], v[158:161], v[190:193], v[2:5]
	v_mfma_f32_16x16x32_bf16 v[2:5], v[162:165], v[194:197], v[2:5]
	v_mfma_f32_16x16x32_bf16 v[70:73], v[150:153], v[198:201], v[70:73]
	v_mfma_f32_16x16x32_bf16 v[70:73], v[154:157], v[202:205], v[70:73]
	v_mfma_f32_16x16x32_bf16 v[6:9], v[158:161], v[198:201], v[6:9]
	v_mfma_f32_16x16x32_bf16 v[6:9], v[162:165], v[202:205], v[6:9]
	v_mfma_f32_16x16x32_bf16 v[74:77], v[150:153], v[206:209], v[74:77]
	v_mfma_f32_16x16x32_bf16 v[74:77], v[154:157], v[210:213], v[74:77]
	v_mfma_f32_16x16x32_bf16 v[10:13], v[158:161], v[206:209], v[10:13]
	v_mfma_f32_16x16x32_bf16 v[10:13], v[162:165], v[210:213], v[10:13]
	v_mfma_f32_16x16x32_bf16 v[98:101], v[166:169], v[182:185], v[98:101]
	v_mfma_f32_16x16x32_bf16 v[98:101], v[170:173], v[186:189], v[98:101]
	v_mfma_f32_16x16x32_bf16 v[34:37], v[174:177], v[182:185], v[34:37]
	v_mfma_f32_16x16x32_bf16 v[34:37], v[178:181], v[186:189], v[34:37]
	v_mfma_f32_16x16x32_bf16 v[82:85], v[166:169], v[190:193], v[82:85]
	v_mfma_f32_16x16x32_bf16 v[82:85], v[170:173], v[194:197], v[82:85]
	v_mfma_f32_16x16x32_bf16 v[18:21], v[174:177], v[190:193], v[18:21]
	v_mfma_f32_16x16x32_bf16 v[18:21], v[178:181], v[194:197], v[18:21]
	v_mfma_f32_16x16x32_bf16 v[86:89], v[166:169], v[198:201], v[86:89]
	v_mfma_f32_16x16x32_bf16 v[86:89], v[170:173], v[202:205], v[86:89]
	v_mfma_f32_16x16x32_bf16 v[22:25], v[174:177], v[198:201], v[22:25]
	v_mfma_f32_16x16x32_bf16 v[22:25], v[178:181], v[202:205], v[22:25]
	v_mfma_f32_16x16x32_bf16 v[94:97], v[166:169], v[206:209], v[94:97]
	v_mfma_f32_16x16x32_bf16 v[94:97], v[170:173], v[210:213], v[94:97]
	v_mfma_f32_16x16x32_bf16 v[30:33], v[174:177], v[206:209], v[30:33]
	v_mfma_f32_16x16x32_bf16 v[30:33], v[178:181], v[210:213], v[30:33]
	s_barrier
	s_add_i32 s50, s78, s15
	v_lshl_add_u64 v[214:215], v[214:215], 0, s[8:9]
	s_mov_b32 m0, s50
	ds_read_b128 v[182:185], v149 offset:49152
	ds_read_b128 v[186:189], v149 offset:50176
	ds_read_b128 v[190:193], v149 offset:51200
	ds_read_b128 v[194:197], v149 offset:52224
	ds_read_b128 v[198:201], v149 offset:53248
	ds_read_b128 v[202:205], v149 offset:54272
	ds_read_b128 v[206:209], v149 offset:55296
	ds_read_b128 v[210:213], v149 offset:56320
	global_load_lds_dwordx4 v[214:215], off
	s_add_i32 m0, s50, 0x2000
	s_add_u32 s50, s52, 0x40080
	v_lshl_add_u64 v[214:215], v[216:217], 0, s[8:9]
	s_addc_u32 s51, s53, 0
	s_add_i32 s52, s79, s15
	global_load_lds_dwordx4 v[214:215], off
	v_lshl_add_u64 v[214:215], s[50:51], 0, v[228:229]
	s_mov_b32 m0, s52
	s_nop 0
	global_load_lds_dwordx4 v[214:215], off
	v_lshl_add_u64 v[214:215], s[50:51], 0, v[232:233]
	s_add_i32 m0, s52, 0x2000
	s_nop 0
	global_load_lds_dwordx4 v[214:215], off
	v_lshl_add_u64 v[214:215], v[218:219], 0, s[8:9]
	s_mov_b32 m0, s68
	s_nop 0
	global_load_lds_dwordx4 v[214:215], off
	v_lshl_add_u64 v[214:215], v[220:221], 0, s[8:9]
	s_mov_b32 m0, s69
	s_nop 0
	global_load_lds_dwordx4 v[214:215], off
	s_waitcnt vmcnt(8)
	s_waitcnt lgkmcnt(0)
	s_barrier
	v_mfma_f32_16x16x32_bf16 v[90:93], v[150:153], v[182:185], v[90:93]
	v_mfma_f32_16x16x32_bf16 v[90:93], v[154:157], v[186:189], v[90:93]
	v_mfma_f32_16x16x32_bf16 v[26:29], v[158:161], v[182:185], v[26:29]
	v_mfma_f32_16x16x32_bf16 v[26:29], v[162:165], v[186:189], v[26:29]
	v_mfma_f32_16x16x32_bf16 v[102:105], v[150:153], v[190:193], v[102:105]
	v_mfma_f32_16x16x32_bf16 v[102:105], v[154:157], v[194:197], v[102:105]
	v_mfma_f32_16x16x32_bf16 v[38:41], v[158:161], v[190:193], v[38:41]
	v_mfma_f32_16x16x32_bf16 v[38:41], v[162:165], v[194:197], v[38:41]
	v_mfma_f32_16x16x32_bf16 v[106:109], v[150:153], v[198:201], v[106:109]
	v_mfma_f32_16x16x32_bf16 v[106:109], v[154:157], v[202:205], v[106:109]
	v_mfma_f32_16x16x32_bf16 v[42:45], v[158:161], v[198:201], v[42:45]
	v_mfma_f32_16x16x32_bf16 v[42:45], v[162:165], v[202:205], v[42:45]
	v_mfma_f32_16x16x32_bf16 v[110:113], v[150:153], v[206:209], v[110:113]
	v_mfma_f32_16x16x32_bf16 v[110:113], v[154:157], v[210:213], v[110:113]
	v_mfma_f32_16x16x32_bf16 v[46:49], v[158:161], v[206:209], v[46:49]
	v_mfma_f32_16x16x32_bf16 v[46:49], v[162:165], v[210:213], v[46:49]
	v_mfma_f32_16x16x32_bf16 v[114:117], v[166:169], v[182:185], v[114:117]
	v_mfma_f32_16x16x32_bf16 v[114:117], v[170:173], v[186:189], v[114:117]
	v_mfma_f32_16x16x32_bf16 v[50:53], v[174:177], v[182:185], v[50:53]
	v_mfma_f32_16x16x32_bf16 v[50:53], v[178:181], v[186:189], v[50:53]
	v_mfma_f32_16x16x32_bf16 v[118:121], v[166:169], v[190:193], v[118:121]
	v_mfma_f32_16x16x32_bf16 v[118:121], v[170:173], v[194:197], v[118:121]
	v_mfma_f32_16x16x32_bf16 v[54:57], v[174:177], v[190:193], v[54:57]
	v_mfma_f32_16x16x32_bf16 v[54:57], v[178:181], v[194:197], v[54:57]
	v_mfma_f32_16x16x32_bf16 v[122:125], v[166:169], v[198:201], v[122:125]
	v_mfma_f32_16x16x32_bf16 v[122:125], v[170:173], v[202:205], v[122:125]
	v_mfma_f32_16x16x32_bf16 v[58:61], v[174:177], v[198:201], v[58:61]
	v_mfma_f32_16x16x32_bf16 v[58:61], v[178:181], v[202:205], v[58:61]
	v_mfma_f32_16x16x32_bf16 v[126:129], v[166:169], v[206:209], v[126:129]
	v_mfma_f32_16x16x32_bf16 v[126:129], v[170:173], v[210:213], v[126:129]
	v_mfma_f32_16x16x32_bf16 v[62:65], v[174:177], v[206:209], v[62:65]
	v_mfma_f32_16x16x32_bf16 v[62:65], v[178:181], v[210:213], v[62:65]
	s_barrier
	s_add_u32 s34, s34, 0x100
	s_addc_u32 s35, s35, 0
	s_add_u32 s21, s21, 0x100
	s_addc_u32 s23, s23, 0
	s_cmp_ge_i32 s77, s66
	s_mov_b32 s52, s77
	s_cbranch_scc0 .LBB0_872

.LBB0_1009:
	v_add_u32_e32 v0, s64, v187
	ds_read_b128 v[130:133], v0
	ds_read_b128 v[134:137], v0 offset:1024
	ds_read_b128 v[138:141], v0 offset:2048
	ds_read_b128 v[142:145], v0 offset:3072
	v_add_u32_e32 v0, s65, v187
	ds_read_b128 v[146:149], v0
	ds_read_b128 v[150:153], v0 offset:1024
	ds_read_b128 v[178:181], v0 offset:2048
	ds_read_b128 v[182:185], v0 offset:3072
	s_add_i32 s35, s42, 2
	s_add_u32 s43, s36, 0x3fc000
	s_addc_u32 s44, s37, 0
	s_cmp_eq_u32 s61, s42
	s_cselect_b32 s46, s28, s43
	s_cselect_b32 s47, s29, s44
	s_cselect_b32 s44, s30, s11
	s_cselect_b32 s45, s31, s27
	s_add_u32 s42, s46, 0x400000
	s_addc_u32 s43, s47, 0
	v_lshl_add_u64 v[0:1], s[36:37], 0, v[168:169]
	s_add_i32 m0, s51, 0xc000
	ds_read_b128 v[220:223], v215
	ds_read_b128 v[224:227], v215 offset:1024
	ds_read_b128 v[228:231], v215 offset:2048
	ds_read_b128 v[232:235], v215 offset:3072
	ds_read_b128 v[236:239], v215 offset:4096
	ds_read_b128 v[240:243], v215 offset:5120
	ds_read_b128 v[244:247], v215 offset:6144
	ds_read_b128 v[248:251], v215 offset:7168
	global_load_lds_dwordx4 v[0:1], off
	v_lshl_add_u64 v[0:1], s[36:37], 0, v[170:171]
	s_add_i32 m0, s51, 0xe000
	s_nop 0
	global_load_lds_dwordx4 v[0:1], off
	s_waitcnt vmcnt(8)
	s_waitcnt lgkmcnt(0)
	s_barrier
	v_mfma_f32_16x16x32_bf16 v[114:117], v[130:133], v[220:223], v[114:117]
	v_mfma_f32_16x16x32_bf16 v[114:117], v[134:137], v[224:227], v[114:117]
	v_mfma_f32_16x16x32_bf16 v[118:121], v[138:141], v[220:223], v[118:121]
	v_mfma_f32_16x16x32_bf16 v[118:121], v[142:145], v[224:227], v[118:121]
	v_mfma_f32_16x16x32_bf16 v[110:113], v[130:133], v[228:231], v[110:113]
	v_mfma_f32_16x16x32_bf16 v[110:113], v[134:137], v[232:235], v[110:113]
	v_mfma_f32_16x16x32_bf16 v[102:105], v[138:141], v[228:231], v[102:105]
	v_mfma_f32_16x16x32_bf16 v[102:105], v[142:145], v[232:235], v[102:105]
	v_mfma_f32_16x16x32_bf16 v[94:97], v[130:133], v[236:239], v[94:97]
	v_mfma_f32_16x16x32_bf16 v[94:97], v[134:137], v[240:243], v[94:97]
	v_mfma_f32_16x16x32_bf16 v[86:89], v[138:141], v[236:239], v[86:89]
	v_mfma_f32_16x16x32_bf16 v[86:89], v[142:145], v[240:243], v[86:89]
	v_mfma_f32_16x16x32_bf16 v[78:81], v[130:133], v[244:247], v[78:81]
	v_mfma_f32_16x16x32_bf16 v[78:81], v[134:137], v[248:251], v[78:81]
	v_mfma_f32_16x16x32_bf16 v[70:73], v[138:141], v[244:247], v[70:73]
	v_mfma_f32_16x16x32_bf16 v[70:73], v[142:145], v[248:251], v[70:73]
	v_mfma_f32_16x16x32_bf16 v[126:129], v[146:149], v[220:223], v[126:129]
	v_mfma_f32_16x16x32_bf16 v[126:129], v[150:153], v[224:227], v[126:129]
	v_mfma_f32_16x16x32_bf16 v[122:125], v[178:181], v[220:223], v[122:125]
	v_mfma_f32_16x16x32_bf16 v[122:125], v[182:185], v[224:227], v[122:125]
	v_mfma_f32_16x16x32_bf16 v[106:109], v[146:149], v[228:231], v[106:109]
	v_mfma_f32_16x16x32_bf16 v[106:109], v[150:153], v[232:235], v[106:109]
	v_mfma_f32_16x16x32_bf16 v[98:101], v[178:181], v[228:231], v[98:101]
	v_mfma_f32_16x16x32_bf16 v[98:101], v[182:185], v[232:235], v[98:101]
	v_mfma_f32_16x16x32_bf16 v[90:93], v[146:149], v[236:239], v[90:93]
	v_mfma_f32_16x16x32_bf16 v[90:93], v[150:153], v[240:243], v[90:93]
	v_mfma_f32_16x16x32_bf16 v[82:85], v[178:181], v[236:239], v[82:85]
	v_mfma_f32_16x16x32_bf16 v[82:85], v[182:185], v[240:243], v[82:85]
	v_mfma_f32_16x16x32_bf16 v[74:77], v[146:149], v[244:247], v[74:77]
	v_mfma_f32_16x16x32_bf16 v[74:77], v[150:153], v[248:251], v[74:77]
	v_mfma_f32_16x16x32_bf16 v[66:69], v[178:181], v[244:247], v[66:69]
	v_mfma_f32_16x16x32_bf16 v[66:69], v[182:185], v[248:251], v[66:69]
	s_barrier
	s_add_i32 s69, s64, s49
	v_lshl_add_u64 v[252:253], s[44:45], 0, v[156:157]
	s_mov_b32 m0, s69
	ds_read_b128 v[220:223], v215 offset:16384
	ds_read_b128 v[224:227], v215 offset:17408
	ds_read_b128 v[228:231], v215 offset:18432
	ds_read_b128 v[232:235], v215 offset:19456
	ds_read_b128 v[236:239], v215 offset:20480
	ds_read_b128 v[240:243], v215 offset:21504
	ds_read_b128 v[244:247], v215 offset:22528
	ds_read_b128 v[248:251], v215 offset:23552
	global_load_lds_dwordx4 v[252:253], off
	s_add_i32 m0, s69, 0x2000
	s_add_u32 s70, s44, 0xb0000
	v_lshl_add_u64 v[172:173], s[44:45], 0, v[160:161]
	s_addc_u32 s71, s45, 0
	s_add_i32 s69, s65, s49
	global_load_lds_dwordx4 v[172:173], off
	v_lshl_add_u64 v[0:1], s[70:71], 0, v[156:157]
	s_mov_b32 m0, s69
	s_nop 0
	global_load_lds_dwordx4 v[0:1], off
	v_lshl_add_u64 v[0:1], s[70:71], 0, v[160:161]
	s_add_i32 m0, s69, 0x2000
	s_nop 0
	global_load_lds_dwordx4 v[0:1], off
	v_lshl_add_u64 v[0:1], s[46:47], 0, v[154:155]
	s_mov_b32 m0, s51
	s_nop 0
	global_load_lds_dwordx4 v[0:1], off
	v_lshl_add_u64 v[0:1], s[46:47], 0, v[158:159]
	s_mov_b32 m0, s52
	s_nop 0
	global_load_lds_dwordx4 v[0:1], off
	s_waitcnt vmcnt(8)
	s_waitcnt lgkmcnt(0)
	s_barrier
	v_mfma_f32_16x16x32_bf16 v[50:53], v[130:133], v[220:223], v[50:53]
	v_mfma_f32_16x16x32_bf16 v[54:57], v[138:141], v[220:223], v[54:57]
	v_mfma_f32_16x16x32_bf16 v[46:49], v[130:133], v[228:231], v[46:49]
	v_mfma_f32_16x16x32_bf16 v[38:41], v[138:141], v[228:231], v[38:41]
	v_mfma_f32_16x16x32_bf16 v[30:33], v[130:133], v[236:239], v[30:33]
	v_mfma_f32_16x16x32_bf16 v[22:25], v[138:141], v[236:239], v[22:25]
	v_mfma_f32_16x16x32_bf16 v[14:17], v[130:133], v[244:247], v[14:17]
	v_mfma_f32_16x16x32_bf16 v[6:9], v[138:141], v[244:247], v[6:9]
	v_mfma_f32_16x16x32_bf16 v[50:53], v[134:137], v[224:227], v[50:53]
	v_mfma_f32_16x16x32_bf16 v[54:57], v[142:145], v[224:227], v[54:57]
	v_mfma_f32_16x16x32_bf16 v[46:49], v[134:137], v[232:235], v[46:49]
	v_mfma_f32_16x16x32_bf16 v[38:41], v[142:145], v[232:235], v[38:41]
	v_mfma_f32_16x16x32_bf16 v[30:33], v[134:137], v[240:243], v[30:33]
	v_mfma_f32_16x16x32_bf16 v[22:25], v[142:145], v[240:243], v[22:25]
	v_mfma_f32_16x16x32_bf16 v[14:17], v[134:137], v[248:251], v[14:17]
	v_mfma_f32_16x16x32_bf16 v[6:9], v[142:145], v[248:251], v[6:9]
	v_mfma_f32_16x16x32_bf16 v[62:65], v[146:149], v[220:223], v[62:65]
	v_mfma_f32_16x16x32_bf16 v[58:61], v[178:181], v[220:223], v[58:61]
	v_mfma_f32_16x16x32_bf16 v[42:45], v[146:149], v[228:231], v[42:45]
	v_mfma_f32_16x16x32_bf16 v[34:37], v[178:181], v[228:231], v[34:37]
	v_mfma_f32_16x16x32_bf16 v[26:29], v[146:149], v[236:239], v[26:29]
	v_mfma_f32_16x16x32_bf16 v[18:21], v[178:181], v[236:239], v[18:21]
	v_mfma_f32_16x16x32_bf16 v[10:13], v[146:149], v[244:247], v[10:13]
	v_mfma_f32_16x16x32_bf16 v[0:3], v[178:181], v[244:247], v[2:5]
	v_mfma_f32_16x16x32_bf16 v[62:65], v[150:153], v[224:227], v[62:65]
	v_mfma_f32_16x16x32_bf16 v[58:61], v[182:185], v[224:227], v[58:61]
	v_mfma_f32_16x16x32_bf16 v[42:45], v[150:153], v[232:235], v[42:45]
	v_mfma_f32_16x16x32_bf16 v[34:37], v[182:185], v[232:235], v[34:37]
	v_mfma_f32_16x16x32_bf16 v[26:29], v[150:153], v[240:243], v[26:29]
	v_mfma_f32_16x16x32_bf16 v[18:21], v[182:185], v[240:243], v[18:21]
	v_mfma_f32_16x16x32_bf16 v[10:13], v[150:153], v[248:251], v[10:13]
	v_mfma_f32_16x16x32_bf16 v[0:3], v[182:185], v[248:251], v[0:3]
	s_barrier
	s_add_i32 s69, 0, 0x18000
	v_add_u32_e32 v4, s69, v187
	s_add_i32 s70, 0, 0x1c000
	ds_read_b128 v[130:133], v4
	ds_read_b128 v[134:137], v4 offset:1024
	ds_read_b128 v[138:141], v4 offset:2048
	ds_read_b128 v[142:145], v4 offset:3072
	v_add_u32_e32 v4, s70, v187
	ds_read_b128 v[146:149], v4
	ds_read_b128 v[150:153], v4 offset:1024
	ds_read_b128 v[178:181], v4 offset:2048
	ds_read_b128 v[182:185], v4 offset:3072
	s_add_u32 s46, s46, 0x4000
	s_addc_u32 s47, s47, 0
	s_mov_b32 m0, s53
	v_lshl_add_u64 v[4:5], s[46:47], 0, v[154:155]
	ds_read_b128 v[220:223], v215 offset:32768
	ds_read_b128 v[224:227], v215 offset:33792
	ds_read_b128 v[228:231], v215 offset:34816
	ds_read_b128 v[232:235], v215 offset:35840
	ds_read_b128 v[236:239], v215 offset:36864
	ds_read_b128 v[240:243], v215 offset:37888
	ds_read_b128 v[244:247], v215 offset:38912
	ds_read_b128 v[248:251], v215 offset:39936
	global_load_lds_dwordx4 v[4:5], off
	v_lshl_add_u64 v[4:5], s[46:47], 0, v[158:159]
	s_mov_b32 m0, s54
	s_nop 0
	global_load_lds_dwordx4 v[4:5], off
	s_waitcnt vmcnt(8)
	s_waitcnt lgkmcnt(0)
	s_barrier
	v_mfma_f32_16x16x32_bf16 v[114:117], v[130:133], v[220:223], v[114:117]
	v_mfma_f32_16x16x32_bf16 v[114:117], v[134:137], v[224:227], v[114:117]
	v_mfma_f32_16x16x32_bf16 v[118:121], v[138:141], v[220:223], v[118:121]
	v_mfma_f32_16x16x32_bf16 v[118:121], v[142:145], v[224:227], v[118:121]
	v_mfma_f32_16x16x32_bf16 v[110:113], v[130:133], v[228:231], v[110:113]
	v_mfma_f32_16x16x32_bf16 v[110:113], v[134:137], v[232:235], v[110:113]
	v_mfma_f32_16x16x32_bf16 v[102:105], v[138:141], v[228:231], v[102:105]
	v_mfma_f32_16x16x32_bf16 v[102:105], v[142:145], v[232:235], v[102:105]
	v_mfma_f32_16x16x32_bf16 v[94:97], v[130:133], v[236:239], v[94:97]
	v_mfma_f32_16x16x32_bf16 v[94:97], v[134:137], v[240:243], v[94:97]
	v_mfma_f32_16x16x32_bf16 v[86:89], v[138:141], v[236:239], v[86:89]
	v_mfma_f32_16x16x32_bf16 v[86:89], v[142:145], v[240:243], v[86:89]
	v_mfma_f32_16x16x32_bf16 v[78:81], v[130:133], v[244:247], v[78:81]
	v_mfma_f32_16x16x32_bf16 v[78:81], v[134:137], v[248:251], v[78:81]
	v_mfma_f32_16x16x32_bf16 v[70:73], v[138:141], v[244:247], v[70:73]
	v_mfma_f32_16x16x32_bf16 v[70:73], v[142:145], v[248:251], v[70:73]
	v_mfma_f32_16x16x32_bf16 v[126:129], v[146:149], v[220:223], v[126:129]
	v_mfma_f32_16x16x32_bf16 v[126:129], v[150:153], v[224:227], v[126:129]
	v_mfma_f32_16x16x32_bf16 v[122:125], v[178:181], v[220:223], v[122:125]
	v_mfma_f32_16x16x32_bf16 v[122:125], v[182:185], v[224:227], v[122:125]
	v_mfma_f32_16x16x32_bf16 v[106:109], v[146:149], v[228:231], v[106:109]
	v_mfma_f32_16x16x32_bf16 v[106:109], v[150:153], v[232:235], v[106:109]
	v_mfma_f32_16x16x32_bf16 v[98:101], v[178:181], v[228:231], v[98:101]
	v_mfma_f32_16x16x32_bf16 v[98:101], v[182:185], v[232:235], v[98:101]
	v_mfma_f32_16x16x32_bf16 v[90:93], v[146:149], v[236:239], v[90:93]
	v_mfma_f32_16x16x32_bf16 v[90:93], v[150:153], v[240:243], v[90:93]
	v_mfma_f32_16x16x32_bf16 v[82:85], v[178:181], v[236:239], v[82:85]
	v_mfma_f32_16x16x32_bf16 v[82:85], v[182:185], v[240:243], v[82:85]
	v_mfma_f32_16x16x32_bf16 v[74:77], v[146:149], v[244:247], v[74:77]
	v_mfma_f32_16x16x32_bf16 v[74:77], v[150:153], v[248:251], v[74:77]
	v_mfma_f32_16x16x32_bf16 v[66:69], v[178:181], v[244:247], v[66:69]
	v_mfma_f32_16x16x32_bf16 v[66:69], v[182:185], v[248:251], v[66:69]
	s_barrier
	s_add_i32 s46, s69, s49
	v_lshl_add_u64 v[4:5], v[252:253], 0, s[18:19]
	s_mov_b32 m0, s46
	ds_read_b128 v[220:223], v215 offset:49152
	ds_read_b128 v[224:227], v215 offset:50176
	ds_read_b128 v[228:231], v215 offset:51200
	ds_read_b128 v[232:235], v215 offset:52224
	ds_read_b128 v[236:239], v215 offset:53248
	ds_read_b128 v[240:243], v215 offset:54272
	ds_read_b128 v[244:247], v215 offset:55296
	ds_read_b128 v[248:251], v215 offset:56320
	global_load_lds_dwordx4 v[4:5], off
	s_add_i32 m0, s46, 0x2000
	s_add_u32 s44, s44, 0xb0080
	v_lshl_add_u64 v[4:5], v[172:173], 0, s[18:19]
	s_addc_u32 s45, s45, 0
	s_add_i32 s46, s70, s49
	global_load_lds_dwordx4 v[4:5], off
	v_lshl_add_u64 v[4:5], s[44:45], 0, v[156:157]
	s_mov_b32 m0, s46
	s_nop 0
	global_load_lds_dwordx4 v[4:5], off
	v_lshl_add_u64 v[4:5], s[44:45], 0, v[160:161]
	s_add_i32 m0, s46, 0x2000
	s_nop 0
	global_load_lds_dwordx4 v[4:5], off
	v_lshl_add_u64 v[4:5], s[42:43], 0, v[154:155]
	s_mov_b32 m0, s59
	s_nop 0
	global_load_lds_dwordx4 v[4:5], off
	v_lshl_add_u64 v[4:5], s[42:43], 0, v[158:159]
	s_mov_b32 m0, s60
	s_nop 0
	global_load_lds_dwordx4 v[4:5], off
	s_waitcnt vmcnt(8)
	s_waitcnt lgkmcnt(0)
	s_barrier
	v_mfma_f32_16x16x32_bf16 v[50:53], v[130:133], v[220:223], v[50:53]
	v_mfma_f32_16x16x32_bf16 v[54:57], v[138:141], v[220:223], v[54:57]
	v_mfma_f32_16x16x32_bf16 v[46:49], v[130:133], v[228:231], v[46:49]
	v_mfma_f32_16x16x32_bf16 v[38:41], v[138:141], v[228:231], v[38:41]
	v_mfma_f32_16x16x32_bf16 v[30:33], v[130:133], v[236:239], v[30:33]
	v_mfma_f32_16x16x32_bf16 v[22:25], v[138:141], v[236:239], v[22:25]
	v_mfma_f32_16x16x32_bf16 v[14:17], v[130:133], v[244:247], v[14:17]
	v_mfma_f32_16x16x32_bf16 v[4:7], v[138:141], v[244:247], v[6:9]
	v_mfma_f32_16x16x32_bf16 v[50:53], v[134:137], v[224:227], v[50:53]
	v_mfma_f32_16x16x32_bf16 v[54:57], v[142:145], v[224:227], v[54:57]
	v_mfma_f32_16x16x32_bf16 v[46:49], v[134:137], v[232:235], v[46:49]
	v_mfma_f32_16x16x32_bf16 v[38:41], v[142:145], v[232:235], v[38:41]
	v_mfma_f32_16x16x32_bf16 v[30:33], v[134:137], v[240:243], v[30:33]
	v_mfma_f32_16x16x32_bf16 v[22:25], v[142:145], v[240:243], v[22:25]
	v_mfma_f32_16x16x32_bf16 v[14:17], v[134:137], v[248:251], v[14:17]
	v_mfma_f32_16x16x32_bf16 v[6:9], v[142:145], v[248:251], v[4:7]
	v_mfma_f32_16x16x32_bf16 v[62:65], v[146:149], v[220:223], v[62:65]
	v_mfma_f32_16x16x32_bf16 v[58:61], v[178:181], v[220:223], v[58:61]
	v_mfma_f32_16x16x32_bf16 v[42:45], v[146:149], v[228:231], v[42:45]
	v_mfma_f32_16x16x32_bf16 v[34:37], v[178:181], v[228:231], v[34:37]
	v_mfma_f32_16x16x32_bf16 v[26:29], v[146:149], v[236:239], v[26:29]
	v_mfma_f32_16x16x32_bf16 v[18:21], v[178:181], v[236:239], v[18:21]
	v_mfma_f32_16x16x32_bf16 v[10:13], v[146:149], v[244:247], v[10:13]
	v_mfma_f32_16x16x32_bf16 v[0:3], v[178:181], v[244:247], v[0:3]
	v_mfma_f32_16x16x32_bf16 v[62:65], v[150:153], v[224:227], v[62:65]
	v_mfma_f32_16x16x32_bf16 v[58:61], v[182:185], v[224:227], v[58:61]
	v_mfma_f32_16x16x32_bf16 v[42:45], v[150:153], v[232:235], v[42:45]
	v_mfma_f32_16x16x32_bf16 v[34:37], v[182:185], v[232:235], v[34:37]
	v_mfma_f32_16x16x32_bf16 v[26:29], v[150:153], v[240:243], v[26:29]
	v_mfma_f32_16x16x32_bf16 v[18:21], v[182:185], v[240:243], v[18:21]
	v_mfma_f32_16x16x32_bf16 v[10:13], v[150:153], v[248:251], v[10:13]
	v_mfma_f32_16x16x32_bf16 v[2:5], v[182:185], v[248:251], v[0:3]
	s_barrier
	s_add_u32 s11, s11, 0x100
	s_addc_u32 s27, s27, 0
	s_add_u32 s36, s36, 0x800000
	s_addc_u32 s37, s37, 0
	s_cmp_ge_i32 s35, s58
	s_mov_b32 s42, s35
	s_cbranch_scc0 .LBB0_1009
	v_mov_b64_e32 v[234:235], v[174:175]
	s_and_b64 vcc, exec, s[22:23]
	s_cbranch_vccnz .LBB0_980
	s_branch .LBB0_981
